# counted wait: vmcnt(0) at the SwiGLU and projection epilogue heads relaxed to vmcnt(8) so the next unit's DMA prefetch stays in flight
# speedup vs baseline: 1.0008x; 1.0008x over previous
; __device__ __forceinline__ unsigned cvt_pk_bf16(float lo, float hi) { unsigned r; asm volatile("v_cvt_pk_bf16_f32 %0, %1, %2" : "=v"(r) : "v"(lo), "v"(hi)); return r; }
; __device__ __forceinline__ float silu_mul(float g, float u) {
;     const float e = __builtin_amdgcn_exp2f(g * -1.4426950408889634f);
;     return g * __builtin_amdgcn_rcpf(1.0f + e) * u;
; }
;     __device__ __forceinline__ void operator()(const f32x4 (&acc)[2][2][4][2], const Unit& u, int wr, int wc, int fr, int fq, const float (&rv)[8]) const {
;         const int row0 = u.pm * BM + wr * 64 + fr, col0 = u.pn * HALF + wc * 32 + 8 * fq;
; #pragma unroll
;         for (int ai = 0; ai < 2; ++ai)
; #pragma unroll
;             for (int m = 0; m < 4; ++m) {
;                 bf16_t* rowp = O + (size_t)(row0 + ai * HALF + m * 16) * ldc + col0;
;                 const float r = rv[ai * 4 + m];
;                 const f32x4 g0 = acc[ai][0][m][0] * r, g1 = acc[ai][0][m][1] * r, u0 = acc[ai][1][m][0] * r, u1 = acc[ai][1][m][1] * r;
;                 u32x4 w;
;                 w.x = cvt_pk_bf16(silu_mul(g0[0], u0[0]), silu_mul(g0[1], u0[1]));
;                 w.y = cvt_pk_bf16(silu_mul(g0[2], u0[2]), silu_mul(g0[3], u0[3]));
;                 w.z = cvt_pk_bf16(silu_mul(g1[0], u1[0]), silu_mul(g1[1], u1[1]));
;                 w.w = cvt_pk_bf16(silu_mul(g1[2], u1[2]), silu_mul(g1[3], u1[3]));
;                 *(u32x4*)rowp = w;
.LBB0_105:
	s_waitcnt vmcnt(8)
	v_pk_mul_f32 v[124:125], v[158:159], v[124:125] op_sel_hi:[0,1]
	v_mul_f32_e32 v165, 0xbfb8aa3b, v124
	v_exp_f32_e32 v165, v165
	v_mul_f32_e32 v168, 0xbfb8aa3b, v125
	v_exp_f32_e32 v170, v168
	v_pk_mul_f32 v[168:169], v[158:159], v[114:115] op_sel_hi:[0,1]
	v_add_f32_e32 v114, 1.0, v165
	v_rcp_f32_e32 v165, v114
	v_add_f32_e32 v114, 1.0, v170
	v_pk_mul_f32 v[126:127], v[158:159], v[126:127] op_sel_hi:[0,1]
	v_pk_mul_f32 v[116:117], v[158:159], v[116:117] op_sel_hi:[0,1]
	v_rcp_f32_e32 v170, v114
	v_pk_mul_f32 v[114:115], v[158:159], v[112:113] op_sel_hi:[0,1]
	v_mul_f32_e32 v112, v124, v165
	v_mul_f32_e32 v112, v112, v116
	v_mul_f32_e32 v116, 0xbfb8aa3b, v126
	v_mul_f32_e32 v124, 0xbfb8aa3b, v127
	v_exp_f32_e32 v116, v116
	v_exp_f32_e32 v124, v124
	v_mul_f32_e32 v113, v125, v170
	v_mul_f32_e32 v113, v113, v117
	v_add_f32_e32 v116, 1.0, v116
	v_add_f32_e32 v117, 1.0, v124
	v_rcp_f32_e32 v116, v116
	v_rcp_f32_e32 v117, v117
	v_pk_mul_f32 v[120:121], v[158:159], v[120:121] op_sel_hi:[0,1]
	v_pk_mul_f32 v[118:119], v[158:159], v[118:119] op_sel_hi:[0,1]
	v_cvt_pk_bf16_f32 v112, v112, v113
	v_mul_f32_e32 v113, v126, v116
	v_mul_f32_e32 v116, v127, v117
	v_mul_f32_e32 v117, 0xbfb8aa3b, v120
	v_mul_f32_e32 v113, v113, v118
	v_exp_f32_e32 v117, v117
	v_mul_f32_e32 v118, 0xbfb8aa3b, v121
	v_exp_f32_e32 v118, v118
	v_pk_mul_f32 v[122:123], v[158:159], v[122:123] op_sel_hi:[0,1]
	v_add_f32_e32 v117, 1.0, v117
	v_rcp_f32_e32 v117, v117
	v_add_f32_e32 v118, 1.0, v118
	v_rcp_f32_e32 v118, v118
	v_mul_f32_e32 v116, v116, v119
	v_cvt_pk_bf16_f32 v113, v113, v116
	v_mul_f32_e32 v116, v120, v117
	v_mul_f32_e32 v117, 0xbfb8aa3b, v122
	v_mul_f32_e32 v114, v116, v114
	v_mul_f32_e32 v116, v121, v118
	v_exp_f32_e32 v117, v117
	v_mul_f32_e32 v118, 0xbfb8aa3b, v123
	v_exp_f32_e32 v118, v118
	v_mul_f32_e32 v115, v116, v115
	v_add_f32_e32 v116, 1.0, v117
	v_rcp_f32_e32 v116, v116
	v_add_f32_e32 v117, 1.0, v118
	v_rcp_f32_e32 v117, v117
	v_lshl_or_b32 v162, s87, 7, v153
	v_lshl_add_u32 v164, s4, 8, v137
	v_ashrrev_i32_e32 v163, 31, v162
	v_mov_b64_e32 v[160:161], s[14:15]
	v_mad_i64_i32 v[166:167], s[10:11], v164, s86, v[160:161]
	v_lshlrev_b64 v[162:163], 1, v[162:163]
	v_cvt_pk_bf16_f32 v114, v114, v115
	v_mul_f32_e32 v115, v122, v116
	v_lshl_add_u64 v[166:167], v[166:167], 0, v[162:163]
	v_mul_f32_e32 v115, v115, v168
	v_mul_f32_e32 v116, v123, v117
	v_pk_mul_f32 v[108:109], v[156:157], v[108:109] op_sel_hi:[0,1]
	v_mul_f32_e32 v116, v116, v169
	v_cvt_pk_bf16_f32 v115, v115, v116
	global_store_dwordx4 v[166:167], v[112:115], off
	v_pk_mul_f32 v[110:111], v[156:157], v[110:111] op_sel_hi:[0,1]
	v_pk_mul_f32 v[100:101], v[156:157], v[100:101] op_sel_hi:[0,1]
	v_mul_f32_e32 v114, 0xbfb8aa3b, v108
	v_exp_f32_e32 v116, v114
	v_mul_f32_e32 v114, 0xbfb8aa3b, v109
	v_exp_f32_e32 v117, v114
	v_pk_mul_f32 v[114:115], v[156:157], v[98:99] op_sel_hi:[0,1]
	v_add_f32_e32 v98, 1.0, v116
	v_rcp_f32_e32 v116, v98
	v_add_f32_e32 v98, 1.0, v117
	v_rcp_f32_e32 v117, v98
	v_pk_mul_f32 v[98:99], v[156:157], v[96:97] op_sel_hi:[0,1]
	v_mul_f32_e32 v96, v108, v116
	v_mul_f32_e32 v96, v96, v100
	v_mul_f32_e32 v100, 0xbfb8aa3b, v110
	v_mul_f32_e32 v108, 0xbfb8aa3b, v111
	v_exp_f32_e32 v100, v100
	v_exp_f32_e32 v108, v108
	v_mul_f32_e32 v97, v109, v117
	v_mul_f32_e32 v97, v97, v101
	v_add_f32_e32 v100, 1.0, v100
	v_add_f32_e32 v101, 1.0, v108
	v_rcp_f32_e32 v100, v100
	v_rcp_f32_e32 v101, v101
	v_pk_mul_f32 v[104:105], v[156:157], v[104:105] op_sel_hi:[0,1]
	v_pk_mul_f32 v[102:103], v[156:157], v[102:103] op_sel_hi:[0,1]
	v_cvt_pk_bf16_f32 v96, v96, v97
	v_mul_f32_e32 v97, v110, v100
	v_mul_f32_e32 v100, v111, v101
	v_mul_f32_e32 v101, 0xbfb8aa3b, v104
	v_mul_f32_e32 v97, v97, v102
	v_exp_f32_e32 v101, v101
	v_mul_f32_e32 v102, 0xbfb8aa3b, v105
	v_exp_f32_e32 v102, v102
	v_pk_mul_f32 v[106:107], v[156:157], v[106:107] op_sel_hi:[0,1]
	v_add_f32_e32 v101, 1.0, v101
	v_rcp_f32_e32 v101, v101
	v_add_f32_e32 v102, 1.0, v102
	v_rcp_f32_e32 v102, v102
	v_mul_f32_e32 v100, v100, v103
	v_cvt_pk_bf16_f32 v97, v97, v100
	v_mul_f32_e32 v100, v104, v101
	v_mul_f32_e32 v101, 0xbfb8aa3b, v106
	v_mul_f32_e32 v98, v100, v98
	v_mul_f32_e32 v100, v105, v102
	v_exp_f32_e32 v101, v101
	v_mul_f32_e32 v102, 0xbfb8aa3b, v107
	v_exp_f32_e32 v102, v102
	v_mul_f32_e32 v99, v100, v99
	v_add_f32_e32 v100, 1.0, v101
	v_rcp_f32_e32 v100, v100
	v_add_f32_e32 v101, 1.0, v102
	v_rcp_f32_e32 v101, v101
	v_or_b32_e32 v112, 16, v164
	v_mad_i64_i32 v[112:113], s[10:11], v112, s86, v[160:161]
	v_cvt_pk_bf16_f32 v98, v98, v99
	v_mul_f32_e32 v99, v106, v100
	v_lshl_add_u64 v[112:113], v[112:113], 0, v[162:163]
	v_mul_f32_e32 v99, v99, v114
	v_mul_f32_e32 v100, v107, v101
	v_pk_mul_f32 v[92:93], v[154:155], v[92:93] op_sel_hi:[0,1]
	v_mul_f32_e32 v100, v100, v115
	v_cvt_pk_bf16_f32 v99, v99, v100
	global_store_dwordx4 v[112:113], v[96:99], off
	v_pk_mul_f32 v[94:95], v[154:155], v[94:95] op_sel_hi:[0,1]
	v_pk_mul_f32 v[84:85], v[154:155], v[84:85] op_sel_hi:[0,1]
	v_mul_f32_e32 v98, 0xbfb8aa3b, v92
	v_exp_f32_e32 v100, v98
	v_mul_f32_e32 v98, 0xbfb8aa3b, v93
	v_exp_f32_e32 v101, v98
	v_pk_mul_f32 v[98:99], v[154:155], v[82:83] op_sel_hi:[0,1]
	v_add_f32_e32 v82, 1.0, v100
	v_rcp_f32_e32 v100, v82
	v_add_f32_e32 v82, 1.0, v101
	v_rcp_f32_e32 v101, v82
	v_pk_mul_f32 v[82:83], v[154:155], v[80:81] op_sel_hi:[0,1]
	v_mul_f32_e32 v80, v92, v100
	v_mul_f32_e32 v80, v80, v84
	v_mul_f32_e32 v84, 0xbfb8aa3b, v94
	v_mul_f32_e32 v92, 0xbfb8aa3b, v95
	v_exp_f32_e32 v84, v84
	v_exp_f32_e32 v92, v92
	v_mul_f32_e32 v81, v93, v101
	v_mul_f32_e32 v81, v81, v85
	v_add_f32_e32 v84, 1.0, v84
	v_add_f32_e32 v85, 1.0, v92
; __device__ __forceinline__ unsigned cvt_pk_bf16(float lo, float hi) { unsigned r; asm volatile("v_cvt_pk_bf16_f32 %0, %1, %2" : "=v"(r) : "v"(lo), "v"(hi)); return r; }
; __device__ __forceinline__ float silu_mul(float g, float u) {
;     const float e = __builtin_amdgcn_exp2f(g * -1.4426950408889634f);
;     return g * __builtin_amdgcn_rcpf(1.0f + e) * u;
; }
;     __device__ __forceinline__ void operator()(const f32x4 (&acc)[2][2][4][2], const Unit& u, int wr, int wc, int fr, int fq, const float (&rv)[8]) const {
;         const int row0 = u.pm * BM + wr * 64 + fr, col0 = u.pn * HALF + wc * 32 + 8 * fq;
; #pragma unroll
;         for (int ai = 0; ai < 2; ++ai)
; #pragma unroll
;             for (int m = 0; m < 4; ++m) {
;                 bf16_t* rowp = O + (size_t)(row0 + ai * HALF + m * 16) * ldc + col0;
;                 const float r = rv[ai * 4 + m];
;                 const f32x4 g0 = acc[ai][0][m][0] * r, g1 = acc[ai][0][m][1] * r, u0 = acc[ai][1][m][0] * r, u1 = acc[ai][1][m][1] * r;
;                 u32x4 w;
;                 w.x = cvt_pk_bf16(silu_mul(g0[0], u0[0]), silu_mul(g0[1], u0[1]));
;                 w.y = cvt_pk_bf16(silu_mul(g0[2], u0[2]), silu_mul(g0[3], u0[3]));
;                 w.z = cvt_pk_bf16(silu_mul(g1[0], u1[0]), silu_mul(g1[1], u1[1]));
;                 w.w = cvt_pk_bf16(silu_mul(g1[2], u1[2]), silu_mul(g1[3], u1[3]));
;                 *(u32x4*)rowp = w;
	v_rcp_f32_e32 v84, v84
	v_rcp_f32_e32 v85, v85
	v_pk_mul_f32 v[88:89], v[154:155], v[88:89] op_sel_hi:[0,1]
	v_pk_mul_f32 v[86:87], v[154:155], v[86:87] op_sel_hi:[0,1]
	v_cvt_pk_bf16_f32 v80, v80, v81
	v_mul_f32_e32 v81, v94, v84
	v_mul_f32_e32 v84, v95, v85
	v_mul_f32_e32 v85, 0xbfb8aa3b, v88
	v_mul_f32_e32 v81, v81, v86
	v_exp_f32_e32 v85, v85
	v_mul_f32_e32 v86, 0xbfb8aa3b, v89
	v_exp_f32_e32 v86, v86
	v_pk_mul_f32 v[90:91], v[154:155], v[90:91] op_sel_hi:[0,1]
	v_add_f32_e32 v85, 1.0, v85
	v_rcp_f32_e32 v85, v85
	v_add_f32_e32 v86, 1.0, v86
	v_rcp_f32_e32 v86, v86
	v_mul_f32_e32 v84, v84, v87
	v_cvt_pk_bf16_f32 v81, v81, v84
	v_mul_f32_e32 v84, v88, v85
	v_mul_f32_e32 v85, 0xbfb8aa3b, v90
	v_mul_f32_e32 v82, v84, v82
	v_mul_f32_e32 v84, v89, v86
	v_exp_f32_e32 v85, v85
	v_mul_f32_e32 v86, 0xbfb8aa3b, v91
	v_exp_f32_e32 v86, v86
	v_mul_f32_e32 v83, v84, v83
	v_add_f32_e32 v84, 1.0, v85
	v_rcp_f32_e32 v84, v84
	v_add_f32_e32 v85, 1.0, v86
	v_rcp_f32_e32 v85, v85
	v_or_b32_e32 v96, 32, v164
	v_mad_i64_i32 v[96:97], s[10:11], v96, s86, v[160:161]
	v_cvt_pk_bf16_f32 v82, v82, v83
	v_mul_f32_e32 v83, v90, v84
	v_lshl_add_u64 v[96:97], v[96:97], 0, v[162:163]
	v_mul_f32_e32 v83, v83, v98
	v_mul_f32_e32 v84, v91, v85
	v_pk_mul_f32 v[76:77], v[152:153], v[76:77] op_sel_hi:[0,1]
	v_mul_f32_e32 v84, v84, v99
	v_cvt_pk_bf16_f32 v83, v83, v84
	global_store_dwordx4 v[96:97], v[80:83], off
	v_pk_mul_f32 v[78:79], v[152:153], v[78:79] op_sel_hi:[0,1]
	v_pk_mul_f32 v[68:69], v[152:153], v[68:69] op_sel_hi:[0,1]
	v_mul_f32_e32 v82, 0xbfb8aa3b, v76
	v_exp_f32_e32 v84, v82
	v_mul_f32_e32 v82, 0xbfb8aa3b, v77
	v_exp_f32_e32 v85, v82
	v_pk_mul_f32 v[82:83], v[152:153], v[66:67] op_sel_hi:[0,1]
	v_add_f32_e32 v66, 1.0, v84
	v_rcp_f32_e32 v84, v66
	v_add_f32_e32 v66, 1.0, v85
	v_rcp_f32_e32 v85, v66
	v_pk_mul_f32 v[66:67], v[152:153], v[64:65] op_sel_hi:[0,1]
	v_mul_f32_e32 v64, v76, v84
	v_mul_f32_e32 v64, v64, v68
	v_mul_f32_e32 v68, 0xbfb8aa3b, v78
	v_mul_f32_e32 v76, 0xbfb8aa3b, v79
	v_exp_f32_e32 v68, v68
	v_exp_f32_e32 v76, v76
	v_mul_f32_e32 v65, v77, v85
	v_mul_f32_e32 v65, v65, v69
	v_add_f32_e32 v68, 1.0, v68
	v_add_f32_e32 v69, 1.0, v76
	v_rcp_f32_e32 v68, v68
	v_rcp_f32_e32 v69, v69
	v_pk_mul_f32 v[72:73], v[152:153], v[72:73] op_sel_hi:[0,1]
	v_pk_mul_f32 v[70:71], v[152:153], v[70:71] op_sel_hi:[0,1]
	v_cvt_pk_bf16_f32 v64, v64, v65
	v_mul_f32_e32 v65, v78, v68
	v_mul_f32_e32 v68, v79, v69
	v_mul_f32_e32 v69, 0xbfb8aa3b, v72
	v_mul_f32_e32 v65, v65, v70
	v_exp_f32_e32 v69, v69
	v_mul_f32_e32 v70, 0xbfb8aa3b, v73
	v_exp_f32_e32 v70, v70
	v_pk_mul_f32 v[74:75], v[152:153], v[74:75] op_sel_hi:[0,1]
	v_add_f32_e32 v69, 1.0, v69
	v_rcp_f32_e32 v69, v69
	v_add_f32_e32 v70, 1.0, v70
	v_rcp_f32_e32 v70, v70
	v_mul_f32_e32 v68, v68, v71
	v_cvt_pk_bf16_f32 v65, v65, v68
	v_mul_f32_e32 v68, v72, v69
	v_mul_f32_e32 v69, 0xbfb8aa3b, v74
	v_mul_f32_e32 v66, v68, v66
	v_mul_f32_e32 v68, v73, v70
	v_exp_f32_e32 v69, v69
	v_mul_f32_e32 v70, 0xbfb8aa3b, v75
	v_exp_f32_e32 v70, v70
	v_mul_f32_e32 v67, v68, v67
	v_add_f32_e32 v68, 1.0, v69
	v_rcp_f32_e32 v68, v68
	v_add_f32_e32 v69, 1.0, v70
	v_rcp_f32_e32 v69, v69
	v_or_b32_e32 v80, 48, v164
	v_mad_i64_i32 v[80:81], s[10:11], v80, s86, v[160:161]
	v_cvt_pk_bf16_f32 v66, v66, v67
	v_mul_f32_e32 v67, v74, v68
	v_lshl_add_u64 v[80:81], v[80:81], 0, v[162:163]
	v_mul_f32_e32 v67, v67, v82
	v_mul_f32_e32 v68, v75, v69
	v_pk_mul_f32 v[60:61], v[150:151], v[60:61] op_sel_hi:[0,1]
	v_mul_f32_e32 v68, v68, v83
	v_cvt_pk_bf16_f32 v67, v67, v68
	global_store_dwordx4 v[80:81], v[64:67], off
	v_pk_mul_f32 v[62:63], v[150:151], v[62:63] op_sel_hi:[0,1]
	v_pk_mul_f32 v[52:53], v[150:151], v[52:53] op_sel_hi:[0,1]
	v_mul_f32_e32 v66, 0xbfb8aa3b, v60
	v_exp_f32_e32 v68, v66
	v_mul_f32_e32 v66, 0xbfb8aa3b, v61
	v_exp_f32_e32 v69, v66
	v_pk_mul_f32 v[66:67], v[150:151], v[50:51] op_sel_hi:[0,1]
	v_add_f32_e32 v50, 1.0, v68
	v_rcp_f32_e32 v68, v50
	v_add_f32_e32 v50, 1.0, v69
	v_rcp_f32_e32 v69, v50
	v_pk_mul_f32 v[50:51], v[150:151], v[48:49] op_sel_hi:[0,1]
	v_mul_f32_e32 v48, v60, v68
	v_mul_f32_e32 v48, v48, v52
	v_mul_f32_e32 v52, 0xbfb8aa3b, v62
	v_mul_f32_e32 v60, 0xbfb8aa3b, v63
	v_exp_f32_e32 v52, v52
	v_exp_f32_e32 v60, v60
	v_mul_f32_e32 v49, v61, v69
	v_mul_f32_e32 v49, v49, v53
	v_add_f32_e32 v52, 1.0, v52
	v_add_f32_e32 v53, 1.0, v60
	v_rcp_f32_e32 v52, v52
	v_rcp_f32_e32 v53, v53
	v_pk_mul_f32 v[56:57], v[150:151], v[56:57] op_sel_hi:[0,1]
	v_pk_mul_f32 v[54:55], v[150:151], v[54:55] op_sel_hi:[0,1]
	v_cvt_pk_bf16_f32 v48, v48, v49
	v_mul_f32_e32 v49, v62, v52
	v_mul_f32_e32 v52, v63, v53
	v_mul_f32_e32 v53, 0xbfb8aa3b, v56
	v_mul_f32_e32 v49, v49, v54
	v_exp_f32_e32 v53, v53
	v_mul_f32_e32 v54, 0xbfb8aa3b, v57
	v_exp_f32_e32 v54, v54
	v_pk_mul_f32 v[58:59], v[150:151], v[58:59] op_sel_hi:[0,1]
	v_add_f32_e32 v53, 1.0, v53
	v_rcp_f32_e32 v53, v53
	v_add_f32_e32 v54, 1.0, v54
	v_rcp_f32_e32 v54, v54
	v_mul_f32_e32 v52, v52, v55
	v_cvt_pk_bf16_f32 v49, v49, v52
	v_mul_f32_e32 v52, v56, v53
	v_mul_f32_e32 v53, 0xbfb8aa3b, v58
	v_mul_f32_e32 v50, v52, v50
	v_mul_f32_e32 v52, v57, v54
	v_exp_f32_e32 v53, v53
	v_mul_f32_e32 v54, 0xbfb8aa3b, v59
	v_exp_f32_e32 v54, v54
	v_mul_f32_e32 v51, v52, v51
	v_add_f32_e32 v52, 1.0, v53
	v_rcp_f32_e32 v52, v52
	v_add_f32_e32 v53, 1.0, v54
	v_rcp_f32_e32 v53, v53
	v_add_u32_e32 v64, 0x80, v164
	v_mad_i64_i32 v[64:65], s[10:11], v64, s86, v[160:161]
	v_cvt_pk_bf16_f32 v50, v50, v51
	v_mul_f32_e32 v51, v58, v52
	v_lshl_add_u64 v[64:65], v[64:65], 0, v[162:163]
	v_mul_f32_e32 v51, v51, v66
	v_mul_f32_e32 v52, v59, v53
	v_pk_mul_f32 v[44:45], v[148:149], v[44:45] op_sel_hi:[0,1]
; __device__ __forceinline__ unsigned cvt_pk_bf16(float lo, float hi) { unsigned r; asm volatile("v_cvt_pk_bf16_f32 %0, %1, %2" : "=v"(r) : "v"(lo), "v"(hi)); return r; }
; __device__ __forceinline__ float silu_mul(float g, float u) {
;     const float e = __builtin_amdgcn_exp2f(g * -1.4426950408889634f);
;     return g * __builtin_amdgcn_rcpf(1.0f + e) * u;
; }
;     __device__ __forceinline__ void operator()(const f32x4 (&acc)[2][2][4][2], const Unit& u, int wr, int wc, int fr, int fq, const float (&rv)[8]) const {
;         const int row0 = u.pm * BM + wr * 64 + fr, col0 = u.pn * HALF + wc * 32 + 8 * fq;
; #pragma unroll
;         for (int ai = 0; ai < 2; ++ai)
; #pragma unroll
;             for (int m = 0; m < 4; ++m) {
;                 bf16_t* rowp = O + (size_t)(row0 + ai * HALF + m * 16) * ldc + col0;
;                 const float r = rv[ai * 4 + m];
;                 const f32x4 g0 = acc[ai][0][m][0] * r, g1 = acc[ai][0][m][1] * r, u0 = acc[ai][1][m][0] * r, u1 = acc[ai][1][m][1] * r;
;                 u32x4 w;
;                 w.x = cvt_pk_bf16(silu_mul(g0[0], u0[0]), silu_mul(g0[1], u0[1]));
;                 w.y = cvt_pk_bf16(silu_mul(g0[2], u0[2]), silu_mul(g0[3], u0[3]));
;                 w.z = cvt_pk_bf16(silu_mul(g1[0], u1[0]), silu_mul(g1[1], u1[1]));
;                 w.w = cvt_pk_bf16(silu_mul(g1[2], u1[2]), silu_mul(g1[3], u1[3]));
;                 *(u32x4*)rowp = w;
	v_mul_f32_e32 v52, v52, v67
	v_cvt_pk_bf16_f32 v51, v51, v52
	global_store_dwordx4 v[64:65], v[48:51], off
	v_pk_mul_f32 v[46:47], v[148:149], v[46:47] op_sel_hi:[0,1]
	v_pk_mul_f32 v[36:37], v[148:149], v[36:37] op_sel_hi:[0,1]
	v_mul_f32_e32 v50, 0xbfb8aa3b, v44
	v_exp_f32_e32 v52, v50
	v_mul_f32_e32 v50, 0xbfb8aa3b, v45
	v_exp_f32_e32 v53, v50
	v_pk_mul_f32 v[50:51], v[148:149], v[34:35] op_sel_hi:[0,1]
	v_add_f32_e32 v34, 1.0, v52
	v_rcp_f32_e32 v52, v34
	v_add_f32_e32 v34, 1.0, v53
	v_rcp_f32_e32 v53, v34
	v_pk_mul_f32 v[34:35], v[148:149], v[32:33] op_sel_hi:[0,1]
	v_mul_f32_e32 v32, v44, v52
	v_mul_f32_e32 v32, v32, v36
	v_mul_f32_e32 v36, 0xbfb8aa3b, v46
	v_mul_f32_e32 v44, 0xbfb8aa3b, v47
	v_exp_f32_e32 v36, v36
	v_exp_f32_e32 v44, v44
	v_mul_f32_e32 v33, v45, v53
	v_mul_f32_e32 v33, v33, v37
	v_add_f32_e32 v36, 1.0, v36
	v_add_f32_e32 v37, 1.0, v44
	v_rcp_f32_e32 v36, v36
	v_rcp_f32_e32 v37, v37
	v_pk_mul_f32 v[40:41], v[148:149], v[40:41] op_sel_hi:[0,1]
	v_pk_mul_f32 v[38:39], v[148:149], v[38:39] op_sel_hi:[0,1]
	v_cvt_pk_bf16_f32 v32, v32, v33
	v_mul_f32_e32 v33, v46, v36
	v_mul_f32_e32 v36, v47, v37
	v_mul_f32_e32 v37, 0xbfb8aa3b, v40
	v_mul_f32_e32 v33, v33, v38
	v_exp_f32_e32 v37, v37
	v_mul_f32_e32 v38, 0xbfb8aa3b, v41
	v_exp_f32_e32 v38, v38
	v_pk_mul_f32 v[42:43], v[148:149], v[42:43] op_sel_hi:[0,1]
	v_add_f32_e32 v37, 1.0, v37
	v_rcp_f32_e32 v37, v37
	v_add_f32_e32 v38, 1.0, v38
	v_rcp_f32_e32 v38, v38
	v_mul_f32_e32 v36, v36, v39
	v_cvt_pk_bf16_f32 v33, v33, v36
	v_mul_f32_e32 v36, v40, v37
	v_mul_f32_e32 v37, 0xbfb8aa3b, v42
	v_mul_f32_e32 v34, v36, v34
	v_mul_f32_e32 v36, v41, v38
	v_exp_f32_e32 v37, v37
	v_mul_f32_e32 v38, 0xbfb8aa3b, v43
	v_exp_f32_e32 v38, v38
	v_mul_f32_e32 v35, v36, v35
	v_add_f32_e32 v36, 1.0, v37
	v_rcp_f32_e32 v36, v36
	v_add_f32_e32 v37, 1.0, v38
	v_rcp_f32_e32 v37, v37
	v_add_u32_e32 v48, 0x90, v164
	v_mad_i64_i32 v[48:49], s[10:11], v48, s86, v[160:161]
	v_cvt_pk_bf16_f32 v34, v34, v35
	v_mul_f32_e32 v35, v42, v36
	v_lshl_add_u64 v[48:49], v[48:49], 0, v[162:163]
	v_mul_f32_e32 v35, v35, v50
	v_mul_f32_e32 v36, v43, v37
	v_pk_mul_f32 v[28:29], v[146:147], v[28:29] op_sel_hi:[0,1]
	v_mul_f32_e32 v36, v36, v51
	v_cvt_pk_bf16_f32 v35, v35, v36
	global_store_dwordx4 v[48:49], v[32:35], off
	v_pk_mul_f32 v[30:31], v[146:147], v[30:31] op_sel_hi:[0,1]
	v_pk_mul_f32 v[20:21], v[146:147], v[20:21] op_sel_hi:[0,1]
	v_mul_f32_e32 v34, 0xbfb8aa3b, v28
	v_exp_f32_e32 v36, v34
	v_mul_f32_e32 v34, 0xbfb8aa3b, v29
	v_exp_f32_e32 v37, v34
	v_pk_mul_f32 v[34:35], v[146:147], v[18:19] op_sel_hi:[0,1]
	v_add_f32_e32 v18, 1.0, v36
	v_rcp_f32_e32 v36, v18
	v_add_f32_e32 v18, 1.0, v37
	v_rcp_f32_e32 v37, v18
	v_pk_mul_f32 v[18:19], v[146:147], v[16:17] op_sel_hi:[0,1]
	v_mul_f32_e32 v16, v28, v36
	v_mul_f32_e32 v16, v16, v20
	v_mul_f32_e32 v20, 0xbfb8aa3b, v30
	v_mul_f32_e32 v28, 0xbfb8aa3b, v31
	v_exp_f32_e32 v20, v20
	v_exp_f32_e32 v28, v28
	v_mul_f32_e32 v17, v29, v37
	v_mul_f32_e32 v17, v17, v21
	v_add_f32_e32 v20, 1.0, v20
	v_add_f32_e32 v21, 1.0, v28
	v_rcp_f32_e32 v20, v20
	v_rcp_f32_e32 v21, v21
	v_pk_mul_f32 v[24:25], v[146:147], v[24:25] op_sel_hi:[0,1]
	v_pk_mul_f32 v[22:23], v[146:147], v[22:23] op_sel_hi:[0,1]
	v_cvt_pk_bf16_f32 v16, v16, v17
	v_mul_f32_e32 v17, v30, v20
	v_mul_f32_e32 v20, v31, v21
	v_mul_f32_e32 v21, 0xbfb8aa3b, v24
	v_mul_f32_e32 v17, v17, v22
	v_exp_f32_e32 v21, v21
	v_mul_f32_e32 v22, 0xbfb8aa3b, v25
	v_exp_f32_e32 v22, v22
	v_pk_mul_f32 v[26:27], v[146:147], v[26:27] op_sel_hi:[0,1]
	v_add_f32_e32 v21, 1.0, v21
	v_rcp_f32_e32 v21, v21
	v_add_f32_e32 v22, 1.0, v22
	v_rcp_f32_e32 v22, v22
	v_mul_f32_e32 v20, v20, v23
	v_cvt_pk_bf16_f32 v17, v17, v20
	v_mul_f32_e32 v20, v24, v21
	v_mul_f32_e32 v21, 0xbfb8aa3b, v26
	v_mul_f32_e32 v18, v20, v18
	v_mul_f32_e32 v20, v25, v22
	v_exp_f32_e32 v21, v21
	v_mul_f32_e32 v22, 0xbfb8aa3b, v27
	v_exp_f32_e32 v22, v22
	v_mul_f32_e32 v19, v20, v19
	v_add_f32_e32 v20, 1.0, v21
	v_rcp_f32_e32 v20, v20
	v_add_f32_e32 v21, 1.0, v22
	v_rcp_f32_e32 v21, v21
	v_add_u32_e32 v32, 0xa0, v164
	v_mad_i64_i32 v[32:33], s[10:11], v32, s86, v[160:161]
	v_cvt_pk_bf16_f32 v18, v18, v19
	v_mul_f32_e32 v19, v26, v20
	v_lshl_add_u64 v[32:33], v[32:33], 0, v[162:163]
	v_mul_f32_e32 v19, v19, v34
	v_mul_f32_e32 v20, v27, v21
	v_pk_mul_f32 v[12:13], v[136:137], v[12:13] op_sel_hi:[0,1]
	v_mul_f32_e32 v20, v20, v35
	v_cvt_pk_bf16_f32 v19, v19, v20
	global_store_dwordx4 v[32:33], v[16:19], off
	v_pk_mul_f32 v[14:15], v[136:137], v[14:15] op_sel_hi:[0,1]
	v_pk_mul_f32 v[4:5], v[136:137], v[4:5] op_sel_hi:[0,1]
	v_mul_f32_e32 v18, 0xbfb8aa3b, v12
	v_exp_f32_e32 v20, v18
	v_mul_f32_e32 v18, 0xbfb8aa3b, v13
	v_exp_f32_e32 v21, v18
	v_pk_mul_f32 v[18:19], v[136:137], v[2:3] op_sel_hi:[0,1]
	v_add_f32_e32 v2, 1.0, v20
	v_rcp_f32_e32 v20, v2
	v_add_f32_e32 v2, 1.0, v21
	v_rcp_f32_e32 v21, v2
	v_pk_mul_f32 v[2:3], v[136:137], v[0:1] op_sel_hi:[0,1]
	v_mul_f32_e32 v0, v12, v20
	v_mul_f32_e32 v0, v0, v4
	v_mul_f32_e32 v4, 0xbfb8aa3b, v14
	v_mul_f32_e32 v12, 0xbfb8aa3b, v15
	v_exp_f32_e32 v4, v4
	v_exp_f32_e32 v12, v12
	v_mul_f32_e32 v1, v13, v21
	v_mul_f32_e32 v1, v1, v5
	v_add_f32_e32 v4, 1.0, v4
	v_add_f32_e32 v5, 1.0, v12
	v_rcp_f32_e32 v4, v4
	v_rcp_f32_e32 v5, v5
	v_pk_mul_f32 v[8:9], v[136:137], v[8:9] op_sel_hi:[0,1]
	v_pk_mul_f32 v[6:7], v[136:137], v[6:7] op_sel_hi:[0,1]
	v_cvt_pk_bf16_f32 v0, v0, v1
	v_mul_f32_e32 v1, v14, v4
	v_mul_f32_e32 v4, v15, v5
	v_mul_f32_e32 v5, 0xbfb8aa3b, v8
	v_mul_f32_e32 v1, v1, v6
	v_exp_f32_e32 v5, v5
	v_mul_f32_e32 v6, 0xbfb8aa3b, v9
	v_exp_f32_e32 v6, v6
	v_pk_mul_f32 v[10:11], v[136:137], v[10:11] op_sel_hi:[0,1]
	v_add_f32_e32 v5, 1.0, v5
	v_rcp_f32_e32 v5, v5
	v_add_f32_e32 v6, 1.0, v6
	v_rcp_f32_e32 v6, v6
	v_mul_f32_e32 v4, v4, v7
	v_cvt_pk_bf16_f32 v1, v1, v4
	v_mul_f32_e32 v4, v8, v5
	v_mul_f32_e32 v5, 0xbfb8aa3b, v10
	v_mul_f32_e32 v2, v4, v2
	v_mul_f32_e32 v4, v9, v6
	v_exp_f32_e32 v5, v5
	v_mul_f32_e32 v6, 0xbfb8aa3b, v11
	v_exp_f32_e32 v6, v6
	v_mul_f32_e32 v3, v4, v3
	v_add_f32_e32 v4, 1.0, v5
	v_rcp_f32_e32 v4, v4
	v_add_f32_e32 v5, 1.0, v6
	v_rcp_f32_e32 v5, v5
	v_add_u32_e32 v16, 0xb0, v164
	v_mad_i64_i32 v[16:17], s[10:11], v16, s86, v[160:161]
	v_cvt_pk_bf16_f32 v2, v2, v3
	v_mul_f32_e32 v3, v10, v4
	v_lshl_add_u64 v[16:17], v[16:17], 0, v[162:163]
	v_mul_f32_e32 v3, v3, v18
	v_mul_f32_e32 v4, v11, v5
	s_andn2_b64 vcc, exec, s[0:1]
	s_mov_b64 s[0:1], -1
	v_mul_f32_e32 v4, v4, v19
	v_cvt_pk_bf16_f32 v3, v3, v4
	global_store_dwordx4 v[16:17], v[0:3], off
	s_cbranch_vccnz .LBB0_98
; #define PG8_BAR __builtin_amdgcn_s_barrier()
;     __device__ __forceinline__ void pre(const Unit& u, int wr, int fr, float (&rv)[8]) const {
; #pragma unroll
;         for (int i = 0; i < 8; ++i) rv[i] = rs[u.pm * BM + wr * 64 + fr + (i >> 2) * HALF + (i & 3) * 16];
;     }
; template <class Epi, class Sched, bool ALIGN_EPI = false, bool SP2 = false>
; __device__ __forceinline__ void gemm_phase(PG8_LAS unsigned char* lds, const Gemm g, const Sched& S, const Epi& E) {
;     ...
;         E.pre(cur, wr, fr, epre);
;         if constexpr (ALIGN_EPI) { if (wr == 1) PG8_BAR; }
	s_nop 0
	v_lshl_add_u32 v0, s54, 8, v137
	v_ashrrev_i32_e32 v1, 31, v0
	v_lshl_add_u64 v[0:1], v[0:1], 2, s[16:17]
	global_load_dword v158, v[0:1], off
	global_load_dword v156, v[0:1], off offset:64
	global_load_dword v154, v[0:1], off offset:128
	global_load_dword v152, v[0:1], off offset:192
	global_load_dword v150, v[0:1], off offset:512
	global_load_dword v148, v[0:1], off offset:576
	global_load_dword v146, v[0:1], off offset:640
	global_load_dword v136, v[0:1], off offset:704
	s_andn2_b64 vcc, exec, s[6:7]
	s_cbranch_vccnz .LBB0_97
	s_barrier
	s_branch .LBB0_97

; #define PG8_LAS __attribute__((address_space(3)))
; __device__ __forceinline__ unsigned cvt_pk_bf16(float lo, float hi) { unsigned r; asm volatile("v_cvt_pk_bf16_f32 %0, %1, %2" : "=v"(r) : "v"(lo), "v"(hi)); return r; }
;     __device__ __forceinline__ void operator()(const f32x4 (&acc)[2][2][4][2], const Unit& u, int wr, int wc, int fr, int fq, const float (&rv)[8]) const {
;     ...
; #pragma unroll
;             for (int ai = 0; ai < 2; ++ai)
; #pragma unroll
;                 for (int bj = 0; bj < 2; ++bj) {
; #pragma unroll
;                     for (int m = 0; m < 4; ++m)
; #pragma unroll
;                         for (int n = 0; n < 2; ++n) {
;                             const f32x4 v = acc[ai][bj][m][n] * rv[ai * 4 + m];
;                             const unsigned p01 = cvt_pk_bf16(v[0], v[1]), p23 = cvt_pk_bf16(v[2], v[3]);
;                             const int token = m * 16 + fr, d = 8 * fq + 4 * n;
;                             PG8_LAS unsigned char* wp = wl + d * 128 + (((token >> 3) ^ fq) << 4) + (token & 7) * 2;
;                             *(PG8_LAS bf16_t*)(wp) = (bf16_t)(p01 & 0xffffu); *(PG8_LAS bf16_t*)(wp + 128) = (bf16_t)(p01 >> 16);
;                             *(PG8_LAS bf16_t*)(wp + 256) = (bf16_t)(p23 & 0xffffu); *(PG8_LAS bf16_t*)(wp + 384) = (bf16_t)(p23 >> 16);
;                         }
;                     const int c0 = colt + bj * HALF + wc * 32, h = (dvh == 128) ? (c0 >> 7) : (c0 >> 6), dd0 = c0 & (dvh - 1);
;                     bf16_t* blk = base + (size_t)h * dvh * S + (size_t)(stw + 2 * ai) * (dvh * 64) + dd0 * 64;
; #pragma unroll
;                     for (int i = 0; i < 4; ++i) {
;                         const int q = lane + 64 * i, d = q >> 3, c = q & 7;
;                         const u32x4 w = *(const PG8_LAS u32x4*)(wl + d * 128 + ((c ^ ((d >> 3) & 7)) << 4));
;                         *(u32x4*)(blk + q * 8) = w;
;                     }
;                 }
.LBB0_337:
	s_waitcnt vmcnt(8)
	v_pk_mul_f32 v[178:179], v[164:165], v[124:125] op_sel_hi:[0,1]
	v_pk_mul_f32 v[166:167], v[164:165], v[126:127] op_sel_hi:[0,1]
	v_cvt_pk_bf16_f32 v178, v178, v179
	v_cvt_pk_bf16_f32 v166, v166, v167
	ds_write_b16 v155, v178
	ds_write_b16_d16_hi v155, v178 offset:128
	ds_write_b16 v155, v166 offset:256
	ds_write_b16_d16_hi v155, v166 offset:384
	v_pk_mul_f32 v[178:179], v[164:165], v[120:121] op_sel_hi:[0,1]
	v_pk_mul_f32 v[166:167], v[164:165], v[122:123] op_sel_hi:[0,1]
	v_cvt_pk_bf16_f32 v178, v178, v179
	v_cvt_pk_bf16_f32 v166, v166, v167
	ds_write_b16 v155, v178 offset:512
	ds_write_b16_d16_hi v155, v178 offset:640
	ds_write_b16 v155, v166 offset:768
	ds_write_b16_d16_hi v155, v166 offset:896
	v_pk_mul_f32 v[178:179], v[162:163], v[116:117] op_sel_hi:[0,1]
	v_pk_mul_f32 v[166:167], v[162:163], v[118:119] op_sel_hi:[0,1]
	v_cvt_pk_bf16_f32 v178, v178, v179
	v_cvt_pk_bf16_f32 v166, v166, v167
	ds_write_b16 v161, v178
	ds_write_b16_d16_hi v161, v178 offset:128
	ds_write_b16 v161, v166 offset:256
	ds_write_b16_d16_hi v161, v166 offset:384
	v_pk_mul_f32 v[178:179], v[162:163], v[112:113] op_sel_hi:[0,1]
	v_pk_mul_f32 v[166:167], v[162:163], v[114:115] op_sel_hi:[0,1]
	v_cvt_pk_bf16_f32 v178, v178, v179
	s_sub_i32 s10, s51, s76
	v_cvt_pk_bf16_f32 v166, v166, v167
	ds_write_b16 v161, v178 offset:512
	ds_write_b16_d16_hi v161, v178 offset:640
	ds_write_b16 v161, v166 offset:768
	ds_write_b16_d16_hi v161, v166 offset:896
	v_pk_mul_f32 v[178:179], v[160:161], v[108:109] op_sel_hi:[0,1]
	s_ashr_i32 s10, s10, 6
	s_add_i32 s85, s11, s96
	s_lshl_b32 s11, s57, 6
	v_pk_mul_f32 v[166:167], v[160:161], v[110:111] op_sel_hi:[0,1]
	v_cvt_pk_bf16_f32 v178, v178, v179
	s_mul_hi_i32 s83, s11, s10
	s_mul_i32 s82, s11, s10
	v_cvt_pk_bf16_f32 v166, v166, v167
	ds_write_b16 v163, v178
	ds_write_b16_d16_hi v163, v178 offset:128
	ds_write_b16 v163, v166 offset:256
	ds_write_b16_d16_hi v163, v166 offset:384
	v_pk_mul_f32 v[178:179], v[160:161], v[104:105] op_sel_hi:[0,1]
	s_add_i32 s84, s57, -1
	s_lshl_b64 s[82:83], s[82:83], 1
	v_pk_mul_f32 v[166:167], v[160:161], v[106:107] op_sel_hi:[0,1]
	v_cvt_pk_bf16_f32 v178, v178, v179
	s_add_u32 vcc_lo, s80, s82
	v_cvt_pk_bf16_f32 v166, v166, v167
	ds_write_b16 v163, v178 offset:512
	ds_write_b16_d16_hi v163, v178 offset:640
	ds_write_b16 v163, v166 offset:768
	ds_write_b16_d16_hi v163, v166 offset:896
	v_pk_mul_f32 v[178:179], v[154:155], v[100:101] op_sel_hi:[0,1]
	s_addc_u32 vcc_hi, s81, s83
	v_pk_mul_f32 v[166:167], v[154:155], v[102:103] op_sel_hi:[0,1]
	v_cvt_pk_bf16_f32 v178, v178, v179
	s_lshr_b32 s55, s85, s67
	s_and_b32 s91, s85, s84
	v_cvt_pk_bf16_f32 v166, v166, v167
	ds_write_b16 v165, v178
	ds_write_b16_d16_hi v165, v178 offset:128
	ds_write_b16 v165, v166 offset:256
	ds_write_b16_d16_hi v165, v166 offset:384
	v_pk_mul_f32 v[178:179], v[154:155], v[96:97] op_sel_hi:[0,1]
	s_and_b64 s[62:63], s[74:75], exec
	v_pk_mul_f32 v[166:167], v[154:155], v[98:99] op_sel_hi:[0,1]
	v_cvt_pk_bf16_f32 v178, v178, v179
	s_mul_hi_u32 s83, s55, s57
	s_mul_i32 s82, s55, s57
	s_cselect_b32 s92, 11, 12
	v_cvt_pk_bf16_f32 v166, v166, v167
	ds_write_b16 v165, v178 offset:512
	ds_write_b16_d16_hi v165, v178 offset:640
	ds_write_b16 v165, v166 offset:768
	ds_write_b16_d16_hi v165, v166 offset:896
	s_lshl_b64 s[62:63], s[82:83], s92
	s_lshl_b64 s[82:83], s[62:63], 1
	ds_read_b128 v[178:181], v168
	s_add_u32 s62, vcc_lo, s82
	s_addc_u32 s63, vcc_hi, s83
	s_lshl_b32 s55, s91, 7
	s_add_u32 s62, s62, s55
	s_addc_u32 s63, s63, 0
	s_waitcnt lgkmcnt(0)
	global_store_dwordx4 v169, v[178:181], s[62:63]
	ds_read_b128 v[178:181], v170
	v_pk_mul_f32 v[166:167], v[164:165], v[70:71] op_sel_hi:[0,1]
	s_addk_i32 s85, 0x80
	s_waitcnt lgkmcnt(0)
	global_store_dwordx4 v171, v[178:181], s[62:63]
	ds_read_b128 v[178:181], v172
	s_waitcnt lgkmcnt(0)
	global_store_dwordx4 v173, v[178:181], s[62:63]
	ds_read_b128 v[178:181], v174
	s_waitcnt lgkmcnt(0)
	global_store_dwordx4 v175, v[178:181], s[62:63]
	s_nop 1
	v_pk_mul_f32 v[178:179], v[164:165], v[68:69] op_sel_hi:[0,1]
	v_cvt_pk_bf16_f32 v178, v178, v179
	v_cvt_pk_bf16_f32 v166, v166, v167
	ds_write_b16 v155, v178
	ds_write_b16_d16_hi v155, v178 offset:128
	ds_write_b16 v155, v166 offset:256
	ds_write_b16_d16_hi v155, v166 offset:384
	v_pk_mul_f32 v[178:179], v[164:165], v[64:65] op_sel_hi:[0,1]
	v_pk_mul_f32 v[166:167], v[164:165], v[66:67] op_sel_hi:[0,1]
	v_cvt_pk_bf16_f32 v178, v178, v179
	v_cvt_pk_bf16_f32 v166, v166, v167
	ds_write_b16 v155, v178 offset:512
	ds_write_b16_d16_hi v155, v178 offset:640
	ds_write_b16 v155, v166 offset:768
	ds_write_b16_d16_hi v155, v166 offset:896
	v_pk_mul_f32 v[178:179], v[162:163], v[52:53] op_sel_hi:[0,1]
	v_pk_mul_f32 v[166:167], v[162:163], v[54:55] op_sel_hi:[0,1]
	v_cvt_pk_bf16_f32 v178, v178, v179
	v_cvt_pk_bf16_f32 v166, v166, v167
	ds_write_b16 v161, v178
	ds_write_b16_d16_hi v161, v178 offset:128
	ds_write_b16 v161, v166 offset:256
	ds_write_b16_d16_hi v161, v166 offset:384
	v_pk_mul_f32 v[178:179], v[162:163], v[48:49] op_sel_hi:[0,1]
	v_pk_mul_f32 v[166:167], v[162:163], v[50:51] op_sel_hi:[0,1]
	v_cvt_pk_bf16_f32 v178, v178, v179
	v_cvt_pk_bf16_f32 v166, v166, v167
	ds_write_b16 v161, v178 offset:512
	ds_write_b16_d16_hi v161, v178 offset:640
	ds_write_b16 v161, v166 offset:768
	ds_write_b16_d16_hi v161, v166 offset:896
	v_pk_mul_f32 v[178:179], v[160:161], v[44:45] op_sel_hi:[0,1]
	v_pk_mul_f32 v[166:167], v[160:161], v[46:47] op_sel_hi:[0,1]
	v_cvt_pk_bf16_f32 v178, v178, v179
	v_cvt_pk_bf16_f32 v166, v166, v167
	ds_write_b16 v163, v178
	ds_write_b16_d16_hi v163, v178 offset:128
	ds_write_b16 v163, v166 offset:256
; #define PG8_LAS __attribute__((address_space(3)))
; __device__ __forceinline__ unsigned cvt_pk_bf16(float lo, float hi) { unsigned r; asm volatile("v_cvt_pk_bf16_f32 %0, %1, %2" : "=v"(r) : "v"(lo), "v"(hi)); return r; }
;     __device__ __forceinline__ void operator()(const f32x4 (&acc)[2][2][4][2], const Unit& u, int wr, int wc, int fr, int fq, const float (&rv)[8]) const {
;     ...
; #pragma unroll
;             for (int ai = 0; ai < 2; ++ai)
; #pragma unroll
;                 for (int bj = 0; bj < 2; ++bj) {
; #pragma unroll
;                     for (int m = 0; m < 4; ++m)
; #pragma unroll
;                         for (int n = 0; n < 2; ++n) {
;                             const f32x4 v = acc[ai][bj][m][n] * rv[ai * 4 + m];
;                             const unsigned p01 = cvt_pk_bf16(v[0], v[1]), p23 = cvt_pk_bf16(v[2], v[3]);
;                             const int token = m * 16 + fr, d = 8 * fq + 4 * n;
;                             PG8_LAS unsigned char* wp = wl + d * 128 + (((token >> 3) ^ fq) << 4) + (token & 7) * 2;
;                             *(PG8_LAS bf16_t*)(wp) = (bf16_t)(p01 & 0xffffu); *(PG8_LAS bf16_t*)(wp + 128) = (bf16_t)(p01 >> 16);
;                             *(PG8_LAS bf16_t*)(wp + 256) = (bf16_t)(p23 & 0xffffu); *(PG8_LAS bf16_t*)(wp + 384) = (bf16_t)(p23 >> 16);
;                         }
;                     const int c0 = colt + bj * HALF + wc * 32, h = (dvh == 128) ? (c0 >> 7) : (c0 >> 6), dd0 = c0 & (dvh - 1);
;                     bf16_t* blk = base + (size_t)h * dvh * S + (size_t)(stw + 2 * ai) * (dvh * 64) + dd0 * 64;
; #pragma unroll
;                     for (int i = 0; i < 4; ++i) {
;                         const int q = lane + 64 * i, d = q >> 3, c = q & 7;
;                         const u32x4 w = *(const PG8_LAS u32x4*)(wl + d * 128 + ((c ^ ((d >> 3) & 7)) << 4));
;                         *(u32x4*)(blk + q * 8) = w;
;                     }
;                 }
	ds_write_b16_d16_hi v163, v166 offset:384
	v_pk_mul_f32 v[178:179], v[160:161], v[40:41] op_sel_hi:[0,1]
	v_pk_mul_f32 v[166:167], v[160:161], v[42:43] op_sel_hi:[0,1]
	v_cvt_pk_bf16_f32 v178, v178, v179
	v_cvt_pk_bf16_f32 v166, v166, v167
	ds_write_b16 v163, v178 offset:512
	ds_write_b16_d16_hi v163, v178 offset:640
	ds_write_b16 v163, v166 offset:768
	ds_write_b16_d16_hi v163, v166 offset:896
	v_pk_mul_f32 v[178:179], v[154:155], v[36:37] op_sel_hi:[0,1]
	v_pk_mul_f32 v[166:167], v[154:155], v[38:39] op_sel_hi:[0,1]
	v_cvt_pk_bf16_f32 v178, v178, v179
	v_cvt_pk_bf16_f32 v166, v166, v167
	ds_write_b16 v165, v178
	ds_write_b16_d16_hi v165, v178 offset:128
	ds_write_b16 v165, v166 offset:256
	ds_write_b16_d16_hi v165, v166 offset:384
	v_pk_mul_f32 v[178:179], v[154:155], v[32:33] op_sel_hi:[0,1]
	s_lshr_b32 s62, s85, s67
	v_pk_mul_f32 v[166:167], v[154:155], v[34:35] op_sel_hi:[0,1]
	v_cvt_pk_bf16_f32 v178, v178, v179
	s_mul_hi_u32 s63, s62, s57
	s_mul_i32 s62, s62, s57
	v_cvt_pk_bf16_f32 v166, v166, v167
	ds_write_b16 v165, v178 offset:512
	ds_write_b16_d16_hi v165, v178 offset:640
	ds_write_b16 v165, v166 offset:768
	ds_write_b16_d16_hi v165, v166 offset:896
	s_lshl_b64 s[62:63], s[62:63], s92
	s_and_b32 s67, s85, s84
	s_lshl_b64 s[84:85], s[62:63], 1
	ds_read_b128 v[178:181], v168
	s_add_u32 s62, vcc_lo, s84
	s_addc_u32 s63, vcc_hi, s85
	s_lshl_b32 s57, s67, 7
	s_add_u32 s62, s62, s57
	s_addc_u32 s63, s63, 0
	s_waitcnt lgkmcnt(0)
	global_store_dwordx4 v169, v[178:181], s[62:63]
	ds_read_b128 v[178:181], v170
	v_pk_mul_f32 v[166:167], v[144:145], v[94:95] op_sel_hi:[0,1]
	s_add_i32 s10, s10, 2
	s_waitcnt lgkmcnt(0)
	global_store_dwordx4 v171, v[178:181], s[62:63]
	ds_read_b128 v[178:181], v172
	s_waitcnt lgkmcnt(0)
	global_store_dwordx4 v173, v[178:181], s[62:63]
	ds_read_b128 v[178:181], v174
	s_waitcnt lgkmcnt(0)
	global_store_dwordx4 v175, v[178:181], s[62:63]
	s_nop 1
	v_pk_mul_f32 v[178:179], v[144:145], v[92:93] op_sel_hi:[0,1]
	v_cvt_pk_bf16_f32 v178, v178, v179
	v_cvt_pk_bf16_f32 v166, v166, v167
	ds_write_b16 v155, v178
	ds_write_b16_d16_hi v155, v178 offset:128
	ds_write_b16 v155, v166 offset:256
	ds_write_b16_d16_hi v155, v166 offset:384
	v_pk_mul_f32 v[178:179], v[144:145], v[88:89] op_sel_hi:[0,1]
	v_pk_mul_f32 v[166:167], v[144:145], v[90:91] op_sel_hi:[0,1]
	v_cvt_pk_bf16_f32 v178, v178, v179
	v_cvt_pk_bf16_f32 v166, v166, v167
	ds_write_b16 v155, v178 offset:512
	ds_write_b16_d16_hi v155, v178 offset:640
	ds_write_b16 v155, v166 offset:768
	ds_write_b16_d16_hi v155, v166 offset:896
	v_pk_mul_f32 v[178:179], v[142:143], v[84:85] op_sel_hi:[0,1]
	v_pk_mul_f32 v[166:167], v[142:143], v[86:87] op_sel_hi:[0,1]
	v_cvt_pk_bf16_f32 v178, v178, v179
	v_cvt_pk_bf16_f32 v166, v166, v167
	ds_write_b16 v161, v178
	ds_write_b16_d16_hi v161, v178 offset:128
	ds_write_b16 v161, v166 offset:256
	ds_write_b16_d16_hi v161, v166 offset:384
	v_pk_mul_f32 v[178:179], v[142:143], v[80:81] op_sel_hi:[0,1]
	v_pk_mul_f32 v[166:167], v[142:143], v[82:83] op_sel_hi:[0,1]
	v_cvt_pk_bf16_f32 v178, v178, v179
	v_cvt_pk_bf16_f32 v166, v166, v167
	ds_write_b16 v161, v178 offset:512
	ds_write_b16_d16_hi v161, v178 offset:640
	ds_write_b16 v161, v166 offset:768
	ds_write_b16_d16_hi v161, v166 offset:896
	v_pk_mul_f32 v[178:179], v[140:141], v[76:77] op_sel_hi:[0,1]
	v_pk_mul_f32 v[166:167], v[140:141], v[78:79] op_sel_hi:[0,1]
	v_cvt_pk_bf16_f32 v178, v178, v179
	v_cvt_pk_bf16_f32 v166, v166, v167
	ds_write_b16 v163, v178
	ds_write_b16_d16_hi v163, v178 offset:128
	ds_write_b16 v163, v166 offset:256
	ds_write_b16_d16_hi v163, v166 offset:384
	v_pk_mul_f32 v[178:179], v[140:141], v[72:73] op_sel_hi:[0,1]
	v_pk_mul_f32 v[166:167], v[140:141], v[74:75] op_sel_hi:[0,1]
	v_cvt_pk_bf16_f32 v178, v178, v179
	v_cvt_pk_bf16_f32 v166, v166, v167
	ds_write_b16 v163, v178 offset:512
	ds_write_b16_d16_hi v163, v178 offset:640
	ds_write_b16 v163, v166 offset:768
	ds_write_b16_d16_hi v163, v166 offset:896
	v_pk_mul_f32 v[178:179], v[138:139], v[60:61] op_sel_hi:[0,1]
	v_pk_mul_f32 v[166:167], v[138:139], v[62:63] op_sel_hi:[0,1]
	v_cvt_pk_bf16_f32 v178, v178, v179
	s_mul_hi_i32 s63, s11, s10
	s_mul_i32 s62, s11, s10
	v_cvt_pk_bf16_f32 v166, v166, v167
	ds_write_b16 v165, v178
	ds_write_b16_d16_hi v165, v178 offset:128
	ds_write_b16 v165, v166 offset:256
	ds_write_b16_d16_hi v165, v166 offset:384
	v_pk_mul_f32 v[178:179], v[138:139], v[56:57] op_sel_hi:[0,1]
	s_lshl_b64 s[10:11], s[62:63], 1
	v_pk_mul_f32 v[166:167], v[138:139], v[58:59] op_sel_hi:[0,1]
	v_cvt_pk_bf16_f32 v178, v178, v179
	s_add_u32 s10, s80, s10
	v_cvt_pk_bf16_f32 v166, v166, v167
	ds_write_b16 v165, v178 offset:512
	ds_write_b16_d16_hi v165, v178 offset:640
	ds_write_b16 v165, v166 offset:768
	ds_write_b16_d16_hi v165, v166 offset:896
	s_addc_u32 s11, s81, s11
	ds_read_b128 v[178:181], v168
	s_add_u32 s62, s10, s82
	s_addc_u32 s63, s11, s83
	s_add_u32 s62, s62, s55
	s_addc_u32 s63, s63, 0
	s_waitcnt lgkmcnt(0)
; #define PG8_LAS __attribute__((address_space(3)))
; __device__ __forceinline__ unsigned cvt_pk_bf16(float lo, float hi) { unsigned r; asm volatile("v_cvt_pk_bf16_f32 %0, %1, %2" : "=v"(r) : "v"(lo), "v"(hi)); return r; }
;     __device__ __forceinline__ void operator()(const f32x4 (&acc)[2][2][4][2], const Unit& u, int wr, int wc, int fr, int fq, const float (&rv)[8]) const {
;     ...
; #pragma unroll
;             for (int ai = 0; ai < 2; ++ai)
; #pragma unroll
;                 for (int bj = 0; bj < 2; ++bj) {
; #pragma unroll
;                     for (int m = 0; m < 4; ++m)
; #pragma unroll
;                         for (int n = 0; n < 2; ++n) {
;                             const f32x4 v = acc[ai][bj][m][n] * rv[ai * 4 + m];
;                             const unsigned p01 = cvt_pk_bf16(v[0], v[1]), p23 = cvt_pk_bf16(v[2], v[3]);
;                             const int token = m * 16 + fr, d = 8 * fq + 4 * n;
;                             PG8_LAS unsigned char* wp = wl + d * 128 + (((token >> 3) ^ fq) << 4) + (token & 7) * 2;
;                             *(PG8_LAS bf16_t*)(wp) = (bf16_t)(p01 & 0xffffu); *(PG8_LAS bf16_t*)(wp + 128) = (bf16_t)(p01 >> 16);
;                             *(PG8_LAS bf16_t*)(wp + 256) = (bf16_t)(p23 & 0xffffu); *(PG8_LAS bf16_t*)(wp + 384) = (bf16_t)(p23 >> 16);
;                         }
;                     const int c0 = colt + bj * HALF + wc * 32, h = (dvh == 128) ? (c0 >> 7) : (c0 >> 6), dd0 = c0 & (dvh - 1);
;                     bf16_t* blk = base + (size_t)h * dvh * S + (size_t)(stw + 2 * ai) * (dvh * 64) + dd0 * 64;
; #pragma unroll
;                     for (int i = 0; i < 4; ++i) {
;                         const int q = lane + 64 * i, d = q >> 3, c = q & 7;
;                         const u32x4 w = *(const PG8_LAS u32x4*)(wl + d * 128 + ((c ^ ((d >> 3) & 7)) << 4));
;                         *(u32x4*)(blk + q * 8) = w;
;                     }
;                 }
	global_store_dwordx4 v169, v[178:181], s[62:63]
	ds_read_b128 v[178:181], v170
	v_pk_mul_f32 v[166:167], v[144:145], v[30:31] op_sel_hi:[0,1]
	s_add_u32 s10, s10, s84
	s_addc_u32 s11, s11, s85
	s_add_u32 s10, s10, s57
	s_waitcnt lgkmcnt(0)
	global_store_dwordx4 v171, v[178:181], s[62:63]
	ds_read_b128 v[178:181], v172
	s_addc_u32 s11, s11, 0
	s_waitcnt lgkmcnt(0)
	global_store_dwordx4 v173, v[178:181], s[62:63]
	ds_read_b128 v[178:181], v174
	s_waitcnt lgkmcnt(0)
	global_store_dwordx4 v175, v[178:181], s[62:63]
	s_nop 1
	v_pk_mul_f32 v[178:179], v[144:145], v[28:29] op_sel_hi:[0,1]
	v_cvt_pk_bf16_f32 v178, v178, v179
	v_cvt_pk_bf16_f32 v166, v166, v167
	ds_write_b16 v155, v178
	ds_write_b16_d16_hi v155, v178 offset:128
	ds_write_b16 v155, v166 offset:256
	ds_write_b16_d16_hi v155, v166 offset:384
	v_pk_mul_f32 v[178:179], v[144:145], v[24:25] op_sel_hi:[0,1]
	v_pk_mul_f32 v[166:167], v[144:145], v[26:27] op_sel_hi:[0,1]
	v_cvt_pk_bf16_f32 v178, v178, v179
	v_cvt_pk_bf16_f32 v166, v166, v167
	ds_write_b16 v155, v178 offset:512
	ds_write_b16_d16_hi v155, v178 offset:640
	ds_write_b16 v155, v166 offset:768
	ds_write_b16_d16_hi v155, v166 offset:896
	v_pk_mul_f32 v[178:179], v[142:143], v[20:21] op_sel_hi:[0,1]
	v_pk_mul_f32 v[166:167], v[142:143], v[22:23] op_sel_hi:[0,1]
	v_cvt_pk_bf16_f32 v178, v178, v179
	v_cvt_pk_bf16_f32 v166, v166, v167
	ds_write_b16 v161, v178
	ds_write_b16_d16_hi v161, v178 offset:128
	ds_write_b16 v161, v166 offset:256
	ds_write_b16_d16_hi v161, v166 offset:384
	v_pk_mul_f32 v[178:179], v[142:143], v[16:17] op_sel_hi:[0,1]
	v_pk_mul_f32 v[166:167], v[142:143], v[18:19] op_sel_hi:[0,1]
	v_cvt_pk_bf16_f32 v178, v178, v179
	v_cvt_pk_bf16_f32 v166, v166, v167
	ds_write_b16 v161, v178 offset:512
	ds_write_b16_d16_hi v161, v178 offset:640
	ds_write_b16 v161, v166 offset:768
	ds_write_b16_d16_hi v161, v166 offset:896
	v_pk_mul_f32 v[178:179], v[140:141], v[12:13] op_sel_hi:[0,1]
	v_pk_mul_f32 v[166:167], v[140:141], v[14:15] op_sel_hi:[0,1]
	v_cvt_pk_bf16_f32 v178, v178, v179
	v_cvt_pk_bf16_f32 v166, v166, v167
	ds_write_b16 v163, v178
	ds_write_b16_d16_hi v163, v178 offset:128
	ds_write_b16 v163, v166 offset:256
	ds_write_b16_d16_hi v163, v166 offset:384
	v_pk_mul_f32 v[178:179], v[140:141], v[8:9] op_sel_hi:[0,1]
	v_pk_mul_f32 v[166:167], v[140:141], v[10:11] op_sel_hi:[0,1]
	v_cvt_pk_bf16_f32 v178, v178, v179
	v_cvt_pk_bf16_f32 v166, v166, v167
	ds_write_b16 v163, v178 offset:512
	ds_write_b16_d16_hi v163, v178 offset:640
	ds_write_b16 v163, v166 offset:768
	ds_write_b16_d16_hi v163, v166 offset:896
	v_pk_mul_f32 v[178:179], v[138:139], v[4:5] op_sel_hi:[0,1]
	v_pk_mul_f32 v[166:167], v[138:139], v[6:7] op_sel_hi:[0,1]
	v_cvt_pk_bf16_f32 v178, v178, v179
	v_cvt_pk_bf16_f32 v166, v166, v167
	ds_write_b16 v165, v178
	ds_write_b16_d16_hi v165, v178 offset:128
	ds_write_b16 v165, v166 offset:256
	ds_write_b16_d16_hi v165, v166 offset:384
	v_pk_mul_f32 v[178:179], v[138:139], v[0:1] op_sel_hi:[0,1]
	v_pk_mul_f32 v[166:167], v[138:139], v[2:3] op_sel_hi:[0,1]
	v_cvt_pk_bf16_f32 v178, v178, v179
	v_cvt_pk_bf16_f32 v166, v166, v167
	ds_write_b16 v165, v178 offset:512
	ds_write_b16_d16_hi v165, v178 offset:640
	ds_write_b16 v165, v166 offset:768
	ds_write_b16_d16_hi v165, v166 offset:896
	ds_read_b128 v[178:181], v168
	s_waitcnt lgkmcnt(0)
	global_store_dwordx4 v169, v[178:181], s[10:11]
	ds_read_b128 v[178:181], v170
	s_waitcnt lgkmcnt(0)
	global_store_dwordx4 v171, v[178:181], s[10:11]
	ds_read_b128 v[178:181], v172
	s_waitcnt lgkmcnt(0)
	global_store_dwordx4 v173, v[178:181], s[10:11]
	ds_read_b128 v[178:181], v174
	s_waitcnt lgkmcnt(0)
	global_store_dwordx4 v175, v[178:181], s[10:11]
	s_branch .LBB0_335

; __device__ __forceinline__ unsigned cvt_pk_bf16(float lo, float hi) { unsigned r; asm volatile("v_cvt_pk_bf16_f32 %0, %1, %2" : "=v"(r) : "v"(lo), "v"(hi)); return r; }
;     __device__ __forceinline__ void operator()(const f32x4 (&acc)[2][2][4][2], const Unit& u, int wr, int wc, int fr, int fq, const float (&rv)[8]) const {
;     ...
;         if (pn < 8 || (pn >= 12 && pn < 17)) {
;             bf16_t* base; int colt; float sc = 1.f;
;             if (pn < 4) { base = Qda + (size_t)seqbase * 1024; colt = pn * BM; sc = qscale; }
;             else if (pn < 8) { base = Kda + (size_t)seqbase * 1024; colt = (pn - 4) * BM; }
;             else if (pn < 16) { base = Qsw + (size_t)seqbase * 1024; colt = (pn - 12) * BM; sc = qscale; }
;             else { base = Ksw + (size_t)seqbase * 256; colt = 0; }
;             const int d0 = (wc & 1) * 32 + 8 * fq;
; #pragma unroll
;             for (int bj = 0; bj < 2; ++bj) {
;                 bf16_t* hb = base + (size_t)((colt >> 6) + bj * 2 + (wc >> 1)) * 64 * S + d0;
; #pragma unroll
;                 for (int ai = 0; ai < 2; ++ai)
; #pragma unroll
;                     for (int m = 0; m < 4; ++m) {
;                         const float r = rv[ai * 4 + m] * sc;
;                         const f32x4 v0 = acc[ai][bj][m][0] * r, v1 = acc[ai][bj][m][1] * r;
;                         u32x4 w; w.x = cvt_pk_bf16(v0[0], v0[1]); w.y = cvt_pk_bf16(v0[2], v0[3]); w.z = cvt_pk_bf16(v1[0], v1[1]); w.w = cvt_pk_bf16(v1[2], v1[3]);
;                         *(u32x4*)(hb + (size_t)(s0 + ai * HALF + m * 16) * 64) = w;
;                     }
;             }
.LBB0_349:
	s_ashr_i32 s10, s57, 6
	s_add_i32 s10, s10, s52
	s_ashr_i32 s11, s10, 31
	s_lshl_b64 s[56:57], s[10:11], 6
	v_subrev_u32_e32 v178, s76, v139
	s_and_b64 s[10:11], s[74:75], exec
	v_add_u32_e32 v178, s51, v178
	s_cselect_b32 s10, 11, 12
	s_waitcnt vmcnt(8)
	v_mul_f32_e32 v164, s55, v164
	v_lshl_add_u64 v[166:167], s[80:81], 0, v[136:137]
	s_lshl_b64 s[74:75], s[56:57], s10
	v_pk_mul_f32 v[124:125], v[124:125], v[164:165] op_sel_hi:[1,0]
	v_ashrrev_i32_e32 v179, 31, v178
	v_lshl_add_u64 v[180:181], s[74:75], 1, v[166:167]
	v_pk_mul_f32 v[126:127], v[126:127], v[164:165] op_sel_hi:[1,0]
	v_pk_mul_f32 v[182:183], v[122:123], v[164:165] op_sel_hi:[1,0]
	v_pk_mul_f32 v[122:123], v[120:121], v[164:165] op_sel_hi:[1,0]
	v_cvt_pk_bf16_f32 v120, v124, v125
	v_lshlrev_b64 v[124:125], 7, v[178:179]
	v_cvt_pk_bf16_f32 v121, v126, v127
	v_lshl_add_u64 v[126:127], v[180:181], 0, v[124:125]
	v_cvt_pk_bf16_f32 v122, v122, v123
	v_cvt_pk_bf16_f32 v123, v182, v183
	global_store_dwordx4 v[126:127], v[120:123], off
	s_mov_b64 s[74:75], 0x4000
	s_add_u32 s56, s56, 0x80
	v_mul_f32_e32 v120, s55, v162
	v_pk_mul_f32 v[116:117], v[116:117], v[120:121] op_sel_hi:[1,0]
	v_pk_mul_f32 v[122:123], v[114:115], v[120:121] op_sel_hi:[1,0]
	v_pk_mul_f32 v[114:115], v[112:113], v[120:121] op_sel_hi:[1,0]
	v_cvt_pk_bf16_f32 v112, v116, v117
	v_or_b32_e32 v116, 16, v178
	v_ashrrev_i32_e32 v117, 31, v116
	v_pk_mul_f32 v[118:119], v[118:119], v[120:121] op_sel_hi:[1,0]
	v_lshlrev_b64 v[116:117], 7, v[116:117]
	v_cvt_pk_bf16_f32 v113, v118, v119
	v_lshl_add_u64 v[118:119], v[180:181], 0, v[116:117]
	v_cvt_pk_bf16_f32 v114, v114, v115
	v_cvt_pk_bf16_f32 v115, v122, v123
	global_store_dwordx4 v[118:119], v[112:115], off
	s_addc_u32 s57, s57, 0
	s_lshl_b64 s[10:11], s[56:57], s10
	v_mul_f32_e32 v112, s55, v160
	v_pk_mul_f32 v[108:109], v[108:109], v[112:113] op_sel_hi:[1,0]
	v_pk_mul_f32 v[114:115], v[106:107], v[112:113] op_sel_hi:[1,0]
	v_pk_mul_f32 v[106:107], v[104:105], v[112:113] op_sel_hi:[1,0]
	v_cvt_pk_bf16_f32 v104, v108, v109
	v_or_b32_e32 v108, 32, v178
	v_ashrrev_i32_e32 v109, 31, v108
	v_pk_mul_f32 v[110:111], v[110:111], v[112:113] op_sel_hi:[1,0]
	v_lshlrev_b64 v[108:109], 7, v[108:109]
	v_cvt_pk_bf16_f32 v105, v110, v111
	v_lshl_add_u64 v[110:111], v[180:181], 0, v[108:109]
	v_cvt_pk_bf16_f32 v106, v106, v107
	v_cvt_pk_bf16_f32 v107, v114, v115
	global_store_dwordx4 v[110:111], v[104:107], off
	v_pk_mul_f32 v[64:65], v[64:65], v[164:165] op_sel_hi:[1,0]
	v_pk_mul_f32 v[52:53], v[52:53], v[120:121] op_sel_hi:[1,0]
	v_mul_f32_e32 v104, s55, v154
	v_pk_mul_f32 v[100:101], v[100:101], v[104:105] op_sel_hi:[1,0]
	v_pk_mul_f32 v[106:107], v[98:99], v[104:105] op_sel_hi:[1,0]
	v_pk_mul_f32 v[98:99], v[96:97], v[104:105] op_sel_hi:[1,0]
	v_cvt_pk_bf16_f32 v96, v100, v101
	v_or_b32_e32 v100, 48, v178
	v_ashrrev_i32_e32 v101, 31, v100
	v_pk_mul_f32 v[102:103], v[102:103], v[104:105] op_sel_hi:[1,0]
	v_lshlrev_b64 v[100:101], 7, v[100:101]
	v_cvt_pk_bf16_f32 v97, v102, v103
	v_lshl_add_u64 v[102:103], v[180:181], 0, v[100:101]
	v_cvt_pk_bf16_f32 v98, v98, v99
	v_cvt_pk_bf16_f32 v99, v106, v107
	global_store_dwordx4 v[102:103], v[96:99], off
	v_pk_mul_f32 v[66:67], v[66:67], v[164:165] op_sel_hi:[1,0]
	v_pk_mul_f32 v[54:55], v[54:55], v[120:121] op_sel_hi:[1,0]
	v_mul_f32_e32 v96, s55, v144
	v_pk_mul_f32 v[92:93], v[92:93], v[96:97] op_sel_hi:[1,0]
	v_pk_mul_f32 v[94:95], v[94:95], v[96:97] op_sel_hi:[1,0]
	v_pk_mul_f32 v[98:99], v[90:91], v[96:97] op_sel_hi:[1,0]
	v_pk_mul_f32 v[90:91], v[88:89], v[96:97] op_sel_hi:[1,0]
	v_cvt_pk_bf16_f32 v88, v92, v93
	v_lshl_add_u64 v[92:93], v[124:125], 0, s[74:75]
	v_cvt_pk_bf16_f32 v89, v94, v95
	v_lshl_add_u64 v[94:95], v[180:181], 0, v[92:93]
	v_cvt_pk_bf16_f32 v90, v90, v91
	v_cvt_pk_bf16_f32 v91, v98, v99
	global_store_dwordx4 v[94:95], v[88:91], off
	s_mov_b64 s[74:75], 0x4800
	v_pk_mul_f32 v[44:45], v[44:45], v[112:113] op_sel_hi:[1,0]
	v_mul_f32_e32 v88, s55, v142
	v_pk_mul_f32 v[84:85], v[84:85], v[88:89] op_sel_hi:[1,0]
	v_pk_mul_f32 v[86:87], v[86:87], v[88:89] op_sel_hi:[1,0]
	v_pk_mul_f32 v[90:91], v[82:83], v[88:89] op_sel_hi:[1,0]
	v_pk_mul_f32 v[82:83], v[80:81], v[88:89] op_sel_hi:[1,0]
	v_cvt_pk_bf16_f32 v80, v84, v85
	v_lshl_add_u64 v[84:85], v[124:125], 0, s[74:75]
	v_cvt_pk_bf16_f32 v81, v86, v87
	v_lshl_add_u64 v[86:87], v[180:181], 0, v[84:85]
	v_cvt_pk_bf16_f32 v82, v82, v83
	v_cvt_pk_bf16_f32 v83, v90, v91
	global_store_dwordx4 v[86:87], v[80:83], off
	s_mov_b64 s[74:75], 0x5000
	v_pk_mul_f32 v[46:47], v[46:47], v[112:113] op_sel_hi:[1,0]
	v_mul_f32_e32 v80, s55, v140
; __device__ __forceinline__ unsigned cvt_pk_bf16(float lo, float hi) { unsigned r; asm volatile("v_cvt_pk_bf16_f32 %0, %1, %2" : "=v"(r) : "v"(lo), "v"(hi)); return r; }
;     __device__ __forceinline__ void operator()(const f32x4 (&acc)[2][2][4][2], const Unit& u, int wr, int wc, int fr, int fq, const float (&rv)[8]) const {
;     ...
;         if (pn < 8 || (pn >= 12 && pn < 17)) {
;             bf16_t* base; int colt; float sc = 1.f;
;             if (pn < 4) { base = Qda + (size_t)seqbase * 1024; colt = pn * BM; sc = qscale; }
;             else if (pn < 8) { base = Kda + (size_t)seqbase * 1024; colt = (pn - 4) * BM; }
;             else if (pn < 16) { base = Qsw + (size_t)seqbase * 1024; colt = (pn - 12) * BM; sc = qscale; }
;             else { base = Ksw + (size_t)seqbase * 256; colt = 0; }
;             const int d0 = (wc & 1) * 32 + 8 * fq;
; #pragma unroll
;             for (int bj = 0; bj < 2; ++bj) {
;                 bf16_t* hb = base + (size_t)((colt >> 6) + bj * 2 + (wc >> 1)) * 64 * S + d0;
; #pragma unroll
;                 for (int ai = 0; ai < 2; ++ai)
; #pragma unroll
;                     for (int m = 0; m < 4; ++m) {
;                         const float r = rv[ai * 4 + m] * sc;
;                         const f32x4 v0 = acc[ai][bj][m][0] * r, v1 = acc[ai][bj][m][1] * r;
;                         u32x4 w; w.x = cvt_pk_bf16(v0[0], v0[1]); w.y = cvt_pk_bf16(v0[2], v0[3]); w.z = cvt_pk_bf16(v1[0], v1[1]); w.w = cvt_pk_bf16(v1[2], v1[3]);
;                         *(u32x4*)(hb + (size_t)(s0 + ai * HALF + m * 16) * 64) = w;
;                     }
;             }
	v_pk_mul_f32 v[76:77], v[76:77], v[80:81] op_sel_hi:[1,0]
	v_pk_mul_f32 v[78:79], v[78:79], v[80:81] op_sel_hi:[1,0]
	v_pk_mul_f32 v[82:83], v[74:75], v[80:81] op_sel_hi:[1,0]
	v_pk_mul_f32 v[74:75], v[72:73], v[80:81] op_sel_hi:[1,0]
	v_cvt_pk_bf16_f32 v72, v76, v77
	v_lshl_add_u64 v[76:77], v[124:125], 0, s[74:75]
	v_cvt_pk_bf16_f32 v73, v78, v79
	v_lshl_add_u64 v[78:79], v[180:181], 0, v[76:77]
	v_cvt_pk_bf16_f32 v74, v74, v75
	v_cvt_pk_bf16_f32 v75, v82, v83
	global_store_dwordx4 v[78:79], v[72:75], off
	s_mov_b64 s[74:75], 0x5800
	v_pk_mul_f32 v[36:37], v[36:37], v[104:105] op_sel_hi:[1,0]
	v_mul_f32_e32 v72, s55, v138
	v_pk_mul_f32 v[60:61], v[60:61], v[72:73] op_sel_hi:[1,0]
	v_pk_mul_f32 v[62:63], v[62:63], v[72:73] op_sel_hi:[1,0]
	v_pk_mul_f32 v[74:75], v[58:59], v[72:73] op_sel_hi:[1,0]
	v_pk_mul_f32 v[58:59], v[56:57], v[72:73] op_sel_hi:[1,0]
	v_cvt_pk_bf16_f32 v56, v60, v61
	v_lshl_add_u64 v[60:61], v[124:125], 0, s[74:75]
	v_cvt_pk_bf16_f32 v57, v62, v63
	v_cvt_pk_bf16_f32 v58, v58, v59
	v_cvt_pk_bf16_f32 v59, v74, v75
	v_lshl_add_u64 v[62:63], v[180:181], 0, v[60:61]
	global_store_dwordx4 v[62:63], v[56:59], off
	v_lshl_add_u64 v[62:63], s[10:11], 1, v[166:167]
	v_pk_mul_f32 v[38:39], v[38:39], v[104:105] op_sel_hi:[1,0]
	v_pk_mul_f32 v[58:59], v[70:71], v[164:165] op_sel_hi:[1,0]
	v_pk_mul_f32 v[56:57], v[68:69], v[164:165] op_sel_hi:[1,0]
	v_pk_mul_f32 v[28:29], v[28:29], v[96:97] op_sel_hi:[1,0]
	v_cvt_pk_bf16_f32 v56, v56, v57
	v_cvt_pk_bf16_f32 v57, v58, v59
	v_cvt_pk_bf16_f32 v58, v64, v65
	v_lshl_add_u64 v[64:65], v[62:63], 0, v[124:125]
	v_cvt_pk_bf16_f32 v59, v66, v67
	global_store_dwordx4 v[64:65], v[56:59], off
	v_pk_mul_f32 v[30:31], v[30:31], v[96:97] op_sel_hi:[1,0]
	v_pk_mul_f32 v[20:21], v[20:21], v[88:89] op_sel_hi:[1,0]
	v_pk_mul_f32 v[56:57], v[50:51], v[120:121] op_sel_hi:[1,0]
	v_pk_mul_f32 v[50:51], v[48:49], v[120:121] op_sel_hi:[1,0]
	v_cvt_pk_bf16_f32 v48, v52, v53
	v_cvt_pk_bf16_f32 v49, v54, v55
	v_lshl_add_u64 v[52:53], v[62:63], 0, v[116:117]
	v_cvt_pk_bf16_f32 v50, v50, v51
	v_cvt_pk_bf16_f32 v51, v56, v57
	global_store_dwordx4 v[52:53], v[48:51], off
	v_pk_mul_f32 v[22:23], v[22:23], v[88:89] op_sel_hi:[1,0]
	v_pk_mul_f32 v[12:13], v[12:13], v[80:81] op_sel_hi:[1,0]
	v_pk_mul_f32 v[48:49], v[42:43], v[112:113] op_sel_hi:[1,0]
	v_pk_mul_f32 v[42:43], v[40:41], v[112:113] op_sel_hi:[1,0]
	v_cvt_pk_bf16_f32 v40, v44, v45
	v_cvt_pk_bf16_f32 v41, v46, v47
	v_lshl_add_u64 v[44:45], v[62:63], 0, v[108:109]
	v_cvt_pk_bf16_f32 v42, v42, v43
	v_cvt_pk_bf16_f32 v43, v48, v49
	global_store_dwordx4 v[44:45], v[40:43], off
	v_pk_mul_f32 v[14:15], v[14:15], v[80:81] op_sel_hi:[1,0]
	v_pk_mul_f32 v[4:5], v[4:5], v[72:73] op_sel_hi:[1,0]
	v_pk_mul_f32 v[40:41], v[34:35], v[104:105] op_sel_hi:[1,0]
	v_pk_mul_f32 v[34:35], v[32:33], v[104:105] op_sel_hi:[1,0]
	v_cvt_pk_bf16_f32 v32, v36, v37
	v_cvt_pk_bf16_f32 v33, v38, v39
	v_lshl_add_u64 v[36:37], v[62:63], 0, v[100:101]
	v_cvt_pk_bf16_f32 v34, v34, v35
	v_cvt_pk_bf16_f32 v35, v40, v41
	global_store_dwordx4 v[36:37], v[32:35], off
	v_pk_mul_f32 v[6:7], v[6:7], v[72:73] op_sel_hi:[1,0]
	s_nop 0
	v_pk_mul_f32 v[32:33], v[26:27], v[96:97] op_sel_hi:[1,0]
	v_pk_mul_f32 v[26:27], v[24:25], v[96:97] op_sel_hi:[1,0]
	v_cvt_pk_bf16_f32 v24, v28, v29
	v_cvt_pk_bf16_f32 v25, v30, v31
	v_lshl_add_u64 v[28:29], v[62:63], 0, v[92:93]
	v_cvt_pk_bf16_f32 v26, v26, v27
	v_cvt_pk_bf16_f32 v27, v32, v33
	global_store_dwordx4 v[28:29], v[24:27], off
	s_nop 1
	v_pk_mul_f32 v[24:25], v[18:19], v[88:89] op_sel_hi:[1,0]
	v_pk_mul_f32 v[18:19], v[16:17], v[88:89] op_sel_hi:[1,0]
	v_cvt_pk_bf16_f32 v16, v20, v21
	v_cvt_pk_bf16_f32 v17, v22, v23
	v_lshl_add_u64 v[20:21], v[62:63], 0, v[84:85]
	v_cvt_pk_bf16_f32 v18, v18, v19
	v_cvt_pk_bf16_f32 v19, v24, v25
	global_store_dwordx4 v[20:21], v[16:19], off
	s_nop 1
	v_pk_mul_f32 v[16:17], v[10:11], v[80:81] op_sel_hi:[1,0]
	v_pk_mul_f32 v[10:11], v[8:9], v[80:81] op_sel_hi:[1,0]
	v_cvt_pk_bf16_f32 v8, v12, v13
	v_cvt_pk_bf16_f32 v9, v14, v15
	v_lshl_add_u64 v[12:13], v[62:63], 0, v[76:77]
	v_cvt_pk_bf16_f32 v10, v10, v11
	v_cvt_pk_bf16_f32 v11, v16, v17
	global_store_dwordx4 v[12:13], v[8:11], off
	s_nop 1
	v_pk_mul_f32 v[8:9], v[2:3], v[72:73] op_sel_hi:[1,0]
	v_pk_mul_f32 v[2:3], v[0:1], v[72:73] op_sel_hi:[1,0]
	v_cvt_pk_bf16_f32 v0, v4, v5
	v_lshl_add_u64 v[4:5], v[62:63], 0, v[60:61]
	v_cvt_pk_bf16_f32 v1, v6, v7
	v_cvt_pk_bf16_f32 v2, v2, v3
	v_cvt_pk_bf16_f32 v3, v8, v9
	global_store_dwordx4 v[4:5], v[0:3], off
	s_andn2_b64 vcc, exec, s[0:1]
	s_mov_b64 s[0:1], -1
	s_cbranch_vccnz .LBB0_322

; __device__ __forceinline__ unsigned cvt_pk_bf16(float lo, float hi) { unsigned r; asm volatile("v_cvt_pk_bf16_f32 %0, %1, %2" : "=v"(r) : "v"(lo), "v"(hi)); return r; }
; __device__ __forceinline__ float silu_mul(float g, float u) {
;     const float e = __builtin_amdgcn_exp2f(g * -1.4426950408889634f);
;     return g * __builtin_amdgcn_rcpf(1.0f + e) * u;
; }
;     __device__ __forceinline__ void operator()(const f32x4 (&acc)[2][2][4][2], const Unit& u, int wr, int wc, int fr, int fq, const float (&rv)[8]) const {
;         const int row0 = u.pm * BM + wr * 64 + fr, col0 = u.pn * HALF + wc * 32 + 8 * fq;
; #pragma unroll
;         for (int ai = 0; ai < 2; ++ai)
; #pragma unroll
;             for (int m = 0; m < 4; ++m) {
;                 bf16_t* rowp = O + (size_t)(row0 + ai * HALF + m * 16) * ldc + col0;
;                 const float r = rv[ai * 4 + m];
;                 const f32x4 g0 = acc[ai][0][m][0] * r, g1 = acc[ai][0][m][1] * r, u0 = acc[ai][1][m][0] * r, u1 = acc[ai][1][m][1] * r;
;                 u32x4 w;
;                 w.x = cvt_pk_bf16(silu_mul(g0[0], u0[0]), silu_mul(g0[1], u0[1]));
;                 w.y = cvt_pk_bf16(silu_mul(g0[2], u0[2]), silu_mul(g0[3], u0[3]));
;                 w.z = cvt_pk_bf16(silu_mul(g1[0], u1[0]), silu_mul(g1[1], u1[1]));
;                 w.w = cvt_pk_bf16(silu_mul(g1[2], u1[2]), silu_mul(g1[3], u1[3]));
;                 *(u32x4*)rowp = w;
.LBB0_703:
	s_waitcnt vmcnt(8)
	v_pk_mul_f32 v[124:125], v[162:163], v[124:125] op_sel_hi:[0,1]
	v_pk_mul_f32 v[126:127], v[162:163], v[126:127] op_sel_hi:[0,1]
	v_pk_mul_f32 v[122:123], v[162:163], v[122:123] op_sel_hi:[0,1]
	v_pk_mul_f32 v[120:121], v[162:163], v[120:121] op_sel_hi:[0,1]
	v_pk_mul_f32 v[118:119], v[162:163], v[118:119] op_sel_hi:[0,1]
	v_pk_mul_f32 v[116:117], v[162:163], v[116:117] op_sel_hi:[0,1]
	v_mul_f32_e32 v163, 0xbfb8aa3b, v124
	v_exp_f32_e32 v163, v163
	v_mul_f32_e32 v170, 0xbfb8aa3b, v125
	v_exp_f32_e32 v172, v170
	v_lshl_or_b32 v166, s64, 7, v153
	v_pk_mul_f32 v[170:171], v[162:163], v[114:115] op_sel_hi:[0,1]
	v_add_f32_e32 v114, 1.0, v163
	v_rcp_f32_e32 v163, v114
	v_add_f32_e32 v114, 1.0, v172
	v_rcp_f32_e32 v172, v114
	v_lshl_add_u32 v161, s42, 8, v137
	v_pk_mul_f32 v[114:115], v[162:163], v[112:113] op_sel_hi:[0,1]
	v_mul_f32_e32 v112, v124, v163
	v_mul_f32_e32 v112, v112, v116
	v_mul_f32_e32 v116, 0xbfb8aa3b, v126
	v_mul_f32_e32 v124, 0xbfb8aa3b, v127
	v_exp_f32_e32 v116, v116
	v_exp_f32_e32 v124, v124
	v_mul_f32_e32 v113, v125, v172
	v_mul_f32_e32 v113, v113, v117
	v_add_f32_e32 v116, 1.0, v116
	v_add_f32_e32 v117, 1.0, v124
	v_rcp_f32_e32 v116, v116
	v_rcp_f32_e32 v117, v117
	v_cvt_pk_bf16_f32 v112, v112, v113
	v_ashrrev_i32_e32 v167, 31, v166
	v_mul_f32_e32 v113, v126, v116
	v_mul_f32_e32 v116, v127, v117
	v_mul_f32_e32 v117, 0xbfb8aa3b, v120
	v_mul_f32_e32 v113, v113, v118
	v_exp_f32_e32 v117, v117
	v_mul_f32_e32 v118, 0xbfb8aa3b, v121
	v_exp_f32_e32 v118, v118
	v_mul_f32_e32 v116, v116, v119
	v_add_f32_e32 v117, 1.0, v117
	v_rcp_f32_e32 v117, v117
	v_add_f32_e32 v118, 1.0, v118
	v_rcp_f32_e32 v118, v118
	v_cvt_pk_bf16_f32 v113, v113, v116
	v_mul_f32_e32 v116, v120, v117
	v_mul_f32_e32 v117, 0xbfb8aa3b, v122
	v_mul_f32_e32 v114, v116, v114
	v_mul_f32_e32 v116, v121, v118
	v_exp_f32_e32 v117, v117
	v_mul_f32_e32 v118, 0xbfb8aa3b, v123
	v_exp_f32_e32 v118, v118
	v_mul_f32_e32 v115, v116, v115
	v_add_f32_e32 v116, 1.0, v117
	v_rcp_f32_e32 v116, v116
	v_add_f32_e32 v117, 1.0, v118
	v_rcp_f32_e32 v117, v117
	v_mov_b64_e32 v[164:165], s[14:15]
	v_mad_i64_i32 v[168:169], s[10:11], v161, s61, v[164:165]
	v_lshlrev_b64 v[166:167], 1, v[166:167]
	v_cvt_pk_bf16_f32 v114, v114, v115
	v_mul_f32_e32 v115, v122, v116
	v_lshl_add_u64 v[168:169], v[168:169], 0, v[166:167]
	v_mul_f32_e32 v115, v115, v170
	v_mul_f32_e32 v116, v123, v117
	v_pk_mul_f32 v[108:109], v[160:161], v[108:109] op_sel_hi:[0,1]
	v_mul_f32_e32 v116, v116, v171
	v_cvt_pk_bf16_f32 v115, v115, v116
	global_store_dwordx4 v[168:169], v[112:115], off
	v_pk_mul_f32 v[110:111], v[160:161], v[110:111] op_sel_hi:[0,1]
	v_pk_mul_f32 v[100:101], v[160:161], v[100:101] op_sel_hi:[0,1]
	v_mul_f32_e32 v114, 0xbfb8aa3b, v108
	v_exp_f32_e32 v116, v114
	v_mul_f32_e32 v114, 0xbfb8aa3b, v109
	v_exp_f32_e32 v117, v114
	v_pk_mul_f32 v[114:115], v[160:161], v[98:99] op_sel_hi:[0,1]
	v_add_f32_e32 v98, 1.0, v116
	v_rcp_f32_e32 v116, v98
	v_add_f32_e32 v98, 1.0, v117
	v_rcp_f32_e32 v117, v98
	v_pk_mul_f32 v[98:99], v[160:161], v[96:97] op_sel_hi:[0,1]
	v_mul_f32_e32 v96, v108, v116
	v_mul_f32_e32 v96, v96, v100
	v_mul_f32_e32 v100, 0xbfb8aa3b, v110
	v_mul_f32_e32 v108, 0xbfb8aa3b, v111
	v_exp_f32_e32 v100, v100
	v_exp_f32_e32 v108, v108
	v_mul_f32_e32 v97, v109, v117
	v_mul_f32_e32 v97, v97, v101
	v_add_f32_e32 v100, 1.0, v100
	v_add_f32_e32 v101, 1.0, v108
	v_rcp_f32_e32 v100, v100
	v_rcp_f32_e32 v101, v101
	v_pk_mul_f32 v[104:105], v[160:161], v[104:105] op_sel_hi:[0,1]
	v_pk_mul_f32 v[102:103], v[160:161], v[102:103] op_sel_hi:[0,1]
	v_cvt_pk_bf16_f32 v96, v96, v97
	v_mul_f32_e32 v97, v110, v100
	v_mul_f32_e32 v100, v111, v101
	v_mul_f32_e32 v101, 0xbfb8aa3b, v104
	v_mul_f32_e32 v97, v97, v102
	v_exp_f32_e32 v101, v101
	v_mul_f32_e32 v102, 0xbfb8aa3b, v105
	v_exp_f32_e32 v102, v102
	v_pk_mul_f32 v[106:107], v[160:161], v[106:107] op_sel_hi:[0,1]
	v_add_f32_e32 v101, 1.0, v101
	v_rcp_f32_e32 v101, v101
	v_add_f32_e32 v102, 1.0, v102
	v_rcp_f32_e32 v102, v102
	v_mul_f32_e32 v100, v100, v103
	v_cvt_pk_bf16_f32 v97, v97, v100
	v_mul_f32_e32 v100, v104, v101
	v_mul_f32_e32 v101, 0xbfb8aa3b, v106
	v_mul_f32_e32 v98, v100, v98
	v_mul_f32_e32 v100, v105, v102
	v_exp_f32_e32 v101, v101
	v_mul_f32_e32 v102, 0xbfb8aa3b, v107
	v_exp_f32_e32 v102, v102
	v_mul_f32_e32 v99, v100, v99
	v_add_f32_e32 v100, 1.0, v101
	v_rcp_f32_e32 v100, v100
	v_add_f32_e32 v101, 1.0, v102
	v_rcp_f32_e32 v101, v101
	v_or_b32_e32 v112, 16, v161
	v_mad_i64_i32 v[112:113], s[10:11], v112, s61, v[164:165]
	v_cvt_pk_bf16_f32 v98, v98, v99
	v_mul_f32_e32 v99, v106, v100
	v_lshl_add_u64 v[112:113], v[112:113], 0, v[166:167]
	v_mul_f32_e32 v99, v99, v114
	v_mul_f32_e32 v100, v107, v101
	v_pk_mul_f32 v[92:93], v[158:159], v[92:93] op_sel_hi:[0,1]
	v_mul_f32_e32 v100, v100, v115
	v_cvt_pk_bf16_f32 v99, v99, v100
	global_store_dwordx4 v[112:113], v[96:99], off
	v_pk_mul_f32 v[94:95], v[158:159], v[94:95] op_sel_hi:[0,1]
	v_pk_mul_f32 v[84:85], v[158:159], v[84:85] op_sel_hi:[0,1]
	v_mul_f32_e32 v98, 0xbfb8aa3b, v92
	v_exp_f32_e32 v100, v98
	v_mul_f32_e32 v98, 0xbfb8aa3b, v93
	v_exp_f32_e32 v101, v98
	v_pk_mul_f32 v[98:99], v[158:159], v[82:83] op_sel_hi:[0,1]
	v_add_f32_e32 v82, 1.0, v100
	v_rcp_f32_e32 v100, v82
	v_add_f32_e32 v82, 1.0, v101
	v_rcp_f32_e32 v101, v82
	v_pk_mul_f32 v[82:83], v[158:159], v[80:81] op_sel_hi:[0,1]
	v_mul_f32_e32 v80, v92, v100
	v_mul_f32_e32 v80, v80, v84
	v_mul_f32_e32 v84, 0xbfb8aa3b, v94
	v_mul_f32_e32 v92, 0xbfb8aa3b, v95
	v_exp_f32_e32 v84, v84
	v_exp_f32_e32 v92, v92
	v_mul_f32_e32 v81, v93, v101
	v_mul_f32_e32 v81, v81, v85
	v_add_f32_e32 v84, 1.0, v84
	v_add_f32_e32 v85, 1.0, v92
; __device__ __forceinline__ unsigned cvt_pk_bf16(float lo, float hi) { unsigned r; asm volatile("v_cvt_pk_bf16_f32 %0, %1, %2" : "=v"(r) : "v"(lo), "v"(hi)); return r; }
; __device__ __forceinline__ float silu_mul(float g, float u) {
;     const float e = __builtin_amdgcn_exp2f(g * -1.4426950408889634f);
;     return g * __builtin_amdgcn_rcpf(1.0f + e) * u;
; }
;     __device__ __forceinline__ void operator()(const f32x4 (&acc)[2][2][4][2], const Unit& u, int wr, int wc, int fr, int fq, const float (&rv)[8]) const {
;         const int row0 = u.pm * BM + wr * 64 + fr, col0 = u.pn * HALF + wc * 32 + 8 * fq;
; #pragma unroll
;         for (int ai = 0; ai < 2; ++ai)
; #pragma unroll
;             for (int m = 0; m < 4; ++m) {
;                 bf16_t* rowp = O + (size_t)(row0 + ai * HALF + m * 16) * ldc + col0;
;                 const float r = rv[ai * 4 + m];
;                 const f32x4 g0 = acc[ai][0][m][0] * r, g1 = acc[ai][0][m][1] * r, u0 = acc[ai][1][m][0] * r, u1 = acc[ai][1][m][1] * r;
;                 u32x4 w;
;                 w.x = cvt_pk_bf16(silu_mul(g0[0], u0[0]), silu_mul(g0[1], u0[1]));
;                 w.y = cvt_pk_bf16(silu_mul(g0[2], u0[2]), silu_mul(g0[3], u0[3]));
;                 w.z = cvt_pk_bf16(silu_mul(g1[0], u1[0]), silu_mul(g1[1], u1[1]));
;                 w.w = cvt_pk_bf16(silu_mul(g1[2], u1[2]), silu_mul(g1[3], u1[3]));
;                 *(u32x4*)rowp = w;
	v_rcp_f32_e32 v84, v84
	v_rcp_f32_e32 v85, v85
	v_pk_mul_f32 v[88:89], v[158:159], v[88:89] op_sel_hi:[0,1]
	v_pk_mul_f32 v[86:87], v[158:159], v[86:87] op_sel_hi:[0,1]
	v_cvt_pk_bf16_f32 v80, v80, v81
	v_mul_f32_e32 v81, v94, v84
	v_mul_f32_e32 v84, v95, v85
	v_mul_f32_e32 v85, 0xbfb8aa3b, v88
	v_mul_f32_e32 v81, v81, v86
	v_exp_f32_e32 v85, v85
	v_mul_f32_e32 v86, 0xbfb8aa3b, v89
	v_exp_f32_e32 v86, v86
	v_pk_mul_f32 v[90:91], v[158:159], v[90:91] op_sel_hi:[0,1]
	v_add_f32_e32 v85, 1.0, v85
	v_rcp_f32_e32 v85, v85
	v_add_f32_e32 v86, 1.0, v86
	v_rcp_f32_e32 v86, v86
	v_mul_f32_e32 v84, v84, v87
	v_cvt_pk_bf16_f32 v81, v81, v84
	v_mul_f32_e32 v84, v88, v85
	v_mul_f32_e32 v85, 0xbfb8aa3b, v90
	v_mul_f32_e32 v82, v84, v82
	v_mul_f32_e32 v84, v89, v86
	v_exp_f32_e32 v85, v85
	v_mul_f32_e32 v86, 0xbfb8aa3b, v91
	v_exp_f32_e32 v86, v86
	v_mul_f32_e32 v83, v84, v83
	v_add_f32_e32 v84, 1.0, v85
	v_rcp_f32_e32 v84, v84
	v_add_f32_e32 v85, 1.0, v86
	v_rcp_f32_e32 v85, v85
	v_or_b32_e32 v96, 32, v161
	v_mad_i64_i32 v[96:97], s[10:11], v96, s61, v[164:165]
	v_cvt_pk_bf16_f32 v82, v82, v83
	v_mul_f32_e32 v83, v90, v84
	v_lshl_add_u64 v[96:97], v[96:97], 0, v[166:167]
	v_mul_f32_e32 v83, v83, v98
	v_mul_f32_e32 v84, v91, v85
	v_pk_mul_f32 v[76:77], v[156:157], v[76:77] op_sel_hi:[0,1]
	v_mul_f32_e32 v84, v84, v99
	v_cvt_pk_bf16_f32 v83, v83, v84
	global_store_dwordx4 v[96:97], v[80:83], off
	v_pk_mul_f32 v[78:79], v[156:157], v[78:79] op_sel_hi:[0,1]
	v_pk_mul_f32 v[68:69], v[156:157], v[68:69] op_sel_hi:[0,1]
	v_mul_f32_e32 v82, 0xbfb8aa3b, v76
	v_exp_f32_e32 v84, v82
	v_mul_f32_e32 v82, 0xbfb8aa3b, v77
	v_exp_f32_e32 v85, v82
	v_pk_mul_f32 v[82:83], v[156:157], v[66:67] op_sel_hi:[0,1]
	v_add_f32_e32 v66, 1.0, v84
	v_rcp_f32_e32 v84, v66
	v_add_f32_e32 v66, 1.0, v85
	v_rcp_f32_e32 v85, v66
	v_pk_mul_f32 v[66:67], v[156:157], v[64:65] op_sel_hi:[0,1]
	v_mul_f32_e32 v64, v76, v84
	v_mul_f32_e32 v64, v64, v68
	v_mul_f32_e32 v68, 0xbfb8aa3b, v78
	v_mul_f32_e32 v76, 0xbfb8aa3b, v79
	v_exp_f32_e32 v68, v68
	v_exp_f32_e32 v76, v76
	v_mul_f32_e32 v65, v77, v85
	v_mul_f32_e32 v65, v65, v69
	v_add_f32_e32 v68, 1.0, v68
	v_add_f32_e32 v69, 1.0, v76
	v_rcp_f32_e32 v68, v68
	v_rcp_f32_e32 v69, v69
	v_pk_mul_f32 v[72:73], v[156:157], v[72:73] op_sel_hi:[0,1]
	v_pk_mul_f32 v[70:71], v[156:157], v[70:71] op_sel_hi:[0,1]
	v_cvt_pk_bf16_f32 v64, v64, v65
	v_mul_f32_e32 v65, v78, v68
	v_mul_f32_e32 v68, v79, v69
	v_mul_f32_e32 v69, 0xbfb8aa3b, v72
	v_mul_f32_e32 v65, v65, v70
	v_exp_f32_e32 v69, v69
	v_mul_f32_e32 v70, 0xbfb8aa3b, v73
	v_exp_f32_e32 v70, v70
	v_pk_mul_f32 v[74:75], v[156:157], v[74:75] op_sel_hi:[0,1]
	v_add_f32_e32 v69, 1.0, v69
	v_rcp_f32_e32 v69, v69
	v_add_f32_e32 v70, 1.0, v70
	v_rcp_f32_e32 v70, v70
	v_mul_f32_e32 v68, v68, v71
	v_cvt_pk_bf16_f32 v65, v65, v68
	v_mul_f32_e32 v68, v72, v69
	v_mul_f32_e32 v69, 0xbfb8aa3b, v74
	v_mul_f32_e32 v66, v68, v66
	v_mul_f32_e32 v68, v73, v70
	v_exp_f32_e32 v69, v69
	v_mul_f32_e32 v70, 0xbfb8aa3b, v75
	v_exp_f32_e32 v70, v70
	v_mul_f32_e32 v67, v68, v67
	v_add_f32_e32 v68, 1.0, v69
	v_rcp_f32_e32 v68, v68
	v_add_f32_e32 v69, 1.0, v70
	v_rcp_f32_e32 v69, v69
	v_or_b32_e32 v80, 48, v161
	v_mad_i64_i32 v[80:81], s[10:11], v80, s61, v[164:165]
	v_cvt_pk_bf16_f32 v66, v66, v67
	v_mul_f32_e32 v67, v74, v68
	v_lshl_add_u64 v[80:81], v[80:81], 0, v[166:167]
	v_mul_f32_e32 v67, v67, v82
	v_mul_f32_e32 v68, v75, v69
	v_pk_mul_f32 v[60:61], v[154:155], v[60:61] op_sel_hi:[0,1]
	v_mul_f32_e32 v68, v68, v83
	v_cvt_pk_bf16_f32 v67, v67, v68
	global_store_dwordx4 v[80:81], v[64:67], off
	v_pk_mul_f32 v[62:63], v[154:155], v[62:63] op_sel_hi:[0,1]
	v_pk_mul_f32 v[52:53], v[154:155], v[52:53] op_sel_hi:[0,1]
	v_mul_f32_e32 v66, 0xbfb8aa3b, v60
	v_exp_f32_e32 v68, v66
	v_mul_f32_e32 v66, 0xbfb8aa3b, v61
	v_exp_f32_e32 v69, v66
	v_pk_mul_f32 v[66:67], v[154:155], v[50:51] op_sel_hi:[0,1]
	v_add_f32_e32 v50, 1.0, v68
	v_rcp_f32_e32 v68, v50
	v_add_f32_e32 v50, 1.0, v69
	v_rcp_f32_e32 v69, v50
	v_pk_mul_f32 v[50:51], v[154:155], v[48:49] op_sel_hi:[0,1]
	v_mul_f32_e32 v48, v60, v68
	v_mul_f32_e32 v48, v48, v52
	v_mul_f32_e32 v52, 0xbfb8aa3b, v62
	v_mul_f32_e32 v60, 0xbfb8aa3b, v63
	v_exp_f32_e32 v52, v52
	v_exp_f32_e32 v60, v60
	v_mul_f32_e32 v49, v61, v69
	v_mul_f32_e32 v49, v49, v53
	v_add_f32_e32 v52, 1.0, v52
	v_add_f32_e32 v53, 1.0, v60
	v_rcp_f32_e32 v52, v52
	v_rcp_f32_e32 v53, v53
	v_pk_mul_f32 v[56:57], v[154:155], v[56:57] op_sel_hi:[0,1]
	v_pk_mul_f32 v[54:55], v[154:155], v[54:55] op_sel_hi:[0,1]
	v_cvt_pk_bf16_f32 v48, v48, v49
	v_mul_f32_e32 v49, v62, v52
	v_mul_f32_e32 v52, v63, v53
	v_mul_f32_e32 v53, 0xbfb8aa3b, v56
	v_mul_f32_e32 v49, v49, v54
	v_exp_f32_e32 v53, v53
	v_mul_f32_e32 v54, 0xbfb8aa3b, v57
	v_exp_f32_e32 v54, v54
	v_pk_mul_f32 v[58:59], v[154:155], v[58:59] op_sel_hi:[0,1]
	v_add_f32_e32 v53, 1.0, v53
	v_rcp_f32_e32 v53, v53
	v_add_f32_e32 v54, 1.0, v54
	v_rcp_f32_e32 v54, v54
	v_mul_f32_e32 v52, v52, v55
	v_cvt_pk_bf16_f32 v49, v49, v52
	v_mul_f32_e32 v52, v56, v53
	v_mul_f32_e32 v53, 0xbfb8aa3b, v58
	v_mul_f32_e32 v50, v52, v50
	v_mul_f32_e32 v52, v57, v54
	v_exp_f32_e32 v53, v53
	v_mul_f32_e32 v54, 0xbfb8aa3b, v59
	v_exp_f32_e32 v54, v54
	v_mul_f32_e32 v51, v52, v51
	v_add_f32_e32 v52, 1.0, v53
	v_rcp_f32_e32 v52, v52
	v_add_f32_e32 v53, 1.0, v54
	v_rcp_f32_e32 v53, v53
	v_add_u32_e32 v64, 0x80, v161
	v_mad_i64_i32 v[64:65], s[10:11], v64, s61, v[164:165]
	v_cvt_pk_bf16_f32 v50, v50, v51
	v_mul_f32_e32 v51, v58, v52
	v_lshl_add_u64 v[64:65], v[64:65], 0, v[166:167]
	v_mul_f32_e32 v51, v51, v66
	v_mul_f32_e32 v52, v59, v53
	v_pk_mul_f32 v[44:45], v[152:153], v[44:45] op_sel_hi:[0,1]
; __device__ __forceinline__ unsigned cvt_pk_bf16(float lo, float hi) { unsigned r; asm volatile("v_cvt_pk_bf16_f32 %0, %1, %2" : "=v"(r) : "v"(lo), "v"(hi)); return r; }
; __device__ __forceinline__ float silu_mul(float g, float u) {
;     const float e = __builtin_amdgcn_exp2f(g * -1.4426950408889634f);
;     return g * __builtin_amdgcn_rcpf(1.0f + e) * u;
; }
;     __device__ __forceinline__ void operator()(const f32x4 (&acc)[2][2][4][2], const Unit& u, int wr, int wc, int fr, int fq, const float (&rv)[8]) const {
;         const int row0 = u.pm * BM + wr * 64 + fr, col0 = u.pn * HALF + wc * 32 + 8 * fq;
; #pragma unroll
;         for (int ai = 0; ai < 2; ++ai)
; #pragma unroll
;             for (int m = 0; m < 4; ++m) {
;                 bf16_t* rowp = O + (size_t)(row0 + ai * HALF + m * 16) * ldc + col0;
;                 const float r = rv[ai * 4 + m];
;                 const f32x4 g0 = acc[ai][0][m][0] * r, g1 = acc[ai][0][m][1] * r, u0 = acc[ai][1][m][0] * r, u1 = acc[ai][1][m][1] * r;
;                 u32x4 w;
;                 w.x = cvt_pk_bf16(silu_mul(g0[0], u0[0]), silu_mul(g0[1], u0[1]));
;                 w.y = cvt_pk_bf16(silu_mul(g0[2], u0[2]), silu_mul(g0[3], u0[3]));
;                 w.z = cvt_pk_bf16(silu_mul(g1[0], u1[0]), silu_mul(g1[1], u1[1]));
;                 w.w = cvt_pk_bf16(silu_mul(g1[2], u1[2]), silu_mul(g1[3], u1[3]));
;                 *(u32x4*)rowp = w;
	v_mul_f32_e32 v52, v52, v67
	v_cvt_pk_bf16_f32 v51, v51, v52
	global_store_dwordx4 v[64:65], v[48:51], off
	v_pk_mul_f32 v[46:47], v[152:153], v[46:47] op_sel_hi:[0,1]
	v_pk_mul_f32 v[36:37], v[152:153], v[36:37] op_sel_hi:[0,1]
	v_mul_f32_e32 v50, 0xbfb8aa3b, v44
	v_exp_f32_e32 v52, v50
	v_mul_f32_e32 v50, 0xbfb8aa3b, v45
	v_exp_f32_e32 v53, v50
	v_pk_mul_f32 v[50:51], v[152:153], v[34:35] op_sel_hi:[0,1]
	v_add_f32_e32 v34, 1.0, v52
	v_rcp_f32_e32 v52, v34
	v_add_f32_e32 v34, 1.0, v53
	v_rcp_f32_e32 v53, v34
	v_pk_mul_f32 v[34:35], v[152:153], v[32:33] op_sel_hi:[0,1]
	v_mul_f32_e32 v32, v44, v52
	v_mul_f32_e32 v32, v32, v36
	v_mul_f32_e32 v36, 0xbfb8aa3b, v46
	v_mul_f32_e32 v44, 0xbfb8aa3b, v47
	v_exp_f32_e32 v36, v36
	v_exp_f32_e32 v44, v44
	v_mul_f32_e32 v33, v45, v53
	v_mul_f32_e32 v33, v33, v37
	v_add_f32_e32 v36, 1.0, v36
	v_add_f32_e32 v37, 1.0, v44
	v_rcp_f32_e32 v36, v36
	v_rcp_f32_e32 v37, v37
	v_pk_mul_f32 v[40:41], v[152:153], v[40:41] op_sel_hi:[0,1]
	v_pk_mul_f32 v[38:39], v[152:153], v[38:39] op_sel_hi:[0,1]
	v_cvt_pk_bf16_f32 v32, v32, v33
	v_mul_f32_e32 v33, v46, v36
	v_mul_f32_e32 v36, v47, v37
	v_mul_f32_e32 v37, 0xbfb8aa3b, v40
	v_mul_f32_e32 v33, v33, v38
	v_exp_f32_e32 v37, v37
	v_mul_f32_e32 v38, 0xbfb8aa3b, v41
	v_exp_f32_e32 v38, v38
	v_pk_mul_f32 v[42:43], v[152:153], v[42:43] op_sel_hi:[0,1]
	v_add_f32_e32 v37, 1.0, v37
	v_rcp_f32_e32 v37, v37
	v_add_f32_e32 v38, 1.0, v38
	v_rcp_f32_e32 v38, v38
	v_mul_f32_e32 v36, v36, v39
	v_cvt_pk_bf16_f32 v33, v33, v36
	v_mul_f32_e32 v36, v40, v37
	v_mul_f32_e32 v37, 0xbfb8aa3b, v42
	v_mul_f32_e32 v34, v36, v34
	v_mul_f32_e32 v36, v41, v38
	v_exp_f32_e32 v37, v37
	v_mul_f32_e32 v38, 0xbfb8aa3b, v43
	v_exp_f32_e32 v38, v38
	v_mul_f32_e32 v35, v36, v35
	v_add_f32_e32 v36, 1.0, v37
	v_rcp_f32_e32 v36, v36
	v_add_f32_e32 v37, 1.0, v38
	v_rcp_f32_e32 v37, v37
	v_add_u32_e32 v48, 0x90, v161
	v_mad_i64_i32 v[48:49], s[10:11], v48, s61, v[164:165]
	v_cvt_pk_bf16_f32 v34, v34, v35
	v_mul_f32_e32 v35, v42, v36
	v_lshl_add_u64 v[48:49], v[48:49], 0, v[166:167]
	v_mul_f32_e32 v35, v35, v50
	v_mul_f32_e32 v36, v43, v37
	v_pk_mul_f32 v[28:29], v[146:147], v[28:29] op_sel_hi:[0,1]
	v_mul_f32_e32 v36, v36, v51
	v_cvt_pk_bf16_f32 v35, v35, v36
	global_store_dwordx4 v[48:49], v[32:35], off
	v_pk_mul_f32 v[30:31], v[146:147], v[30:31] op_sel_hi:[0,1]
	v_pk_mul_f32 v[20:21], v[146:147], v[20:21] op_sel_hi:[0,1]
	v_mul_f32_e32 v34, 0xbfb8aa3b, v28
	v_exp_f32_e32 v36, v34
	v_mul_f32_e32 v34, 0xbfb8aa3b, v29
	v_exp_f32_e32 v37, v34
	v_pk_mul_f32 v[34:35], v[146:147], v[18:19] op_sel_hi:[0,1]
	v_add_f32_e32 v18, 1.0, v36
	v_rcp_f32_e32 v36, v18
	v_add_f32_e32 v18, 1.0, v37
	v_rcp_f32_e32 v37, v18
	v_pk_mul_f32 v[18:19], v[146:147], v[16:17] op_sel_hi:[0,1]
	v_mul_f32_e32 v16, v28, v36
	v_mul_f32_e32 v16, v16, v20
	v_mul_f32_e32 v20, 0xbfb8aa3b, v30
	v_mul_f32_e32 v28, 0xbfb8aa3b, v31
	v_exp_f32_e32 v20, v20
	v_exp_f32_e32 v28, v28
	v_mul_f32_e32 v17, v29, v37
	v_mul_f32_e32 v17, v17, v21
	v_add_f32_e32 v20, 1.0, v20
	v_add_f32_e32 v21, 1.0, v28
	v_rcp_f32_e32 v20, v20
	v_rcp_f32_e32 v21, v21
	v_pk_mul_f32 v[24:25], v[146:147], v[24:25] op_sel_hi:[0,1]
	v_pk_mul_f32 v[22:23], v[146:147], v[22:23] op_sel_hi:[0,1]
	v_cvt_pk_bf16_f32 v16, v16, v17
	v_mul_f32_e32 v17, v30, v20
	v_mul_f32_e32 v20, v31, v21
	v_mul_f32_e32 v21, 0xbfb8aa3b, v24
	v_mul_f32_e32 v17, v17, v22
	v_exp_f32_e32 v21, v21
	v_mul_f32_e32 v22, 0xbfb8aa3b, v25
	v_exp_f32_e32 v22, v22
	v_pk_mul_f32 v[26:27], v[146:147], v[26:27] op_sel_hi:[0,1]
	v_add_f32_e32 v21, 1.0, v21
	v_rcp_f32_e32 v21, v21
	v_add_f32_e32 v22, 1.0, v22
	v_rcp_f32_e32 v22, v22
	v_mul_f32_e32 v20, v20, v23
	v_cvt_pk_bf16_f32 v17, v17, v20
	v_mul_f32_e32 v20, v24, v21
	v_mul_f32_e32 v21, 0xbfb8aa3b, v26
	v_mul_f32_e32 v18, v20, v18
	v_mul_f32_e32 v20, v25, v22
	v_exp_f32_e32 v21, v21
	v_mul_f32_e32 v22, 0xbfb8aa3b, v27
	v_exp_f32_e32 v22, v22
	v_mul_f32_e32 v19, v20, v19
	v_add_f32_e32 v20, 1.0, v21
	v_rcp_f32_e32 v20, v20
	v_add_f32_e32 v21, 1.0, v22
	v_rcp_f32_e32 v21, v21
	v_add_u32_e32 v32, 0xa0, v161
	v_mad_i64_i32 v[32:33], s[10:11], v32, s61, v[164:165]
	v_cvt_pk_bf16_f32 v18, v18, v19
	v_mul_f32_e32 v19, v26, v20
	v_lshl_add_u64 v[32:33], v[32:33], 0, v[166:167]
	v_mul_f32_e32 v19, v19, v34
	v_mul_f32_e32 v20, v27, v21
	v_pk_mul_f32 v[12:13], v[136:137], v[12:13] op_sel_hi:[0,1]
	v_mul_f32_e32 v20, v20, v35
	v_cvt_pk_bf16_f32 v19, v19, v20
	global_store_dwordx4 v[32:33], v[16:19], off
	v_pk_mul_f32 v[14:15], v[136:137], v[14:15] op_sel_hi:[0,1]
	v_pk_mul_f32 v[4:5], v[136:137], v[4:5] op_sel_hi:[0,1]
	v_mul_f32_e32 v18, 0xbfb8aa3b, v12
	v_exp_f32_e32 v20, v18
	v_mul_f32_e32 v18, 0xbfb8aa3b, v13
	v_exp_f32_e32 v21, v18
	v_pk_mul_f32 v[18:19], v[136:137], v[2:3] op_sel_hi:[0,1]
	v_add_f32_e32 v2, 1.0, v20
	v_rcp_f32_e32 v20, v2
	v_add_f32_e32 v2, 1.0, v21
	v_rcp_f32_e32 v21, v2
	v_pk_mul_f32 v[2:3], v[136:137], v[0:1] op_sel_hi:[0,1]
	v_mul_f32_e32 v0, v12, v20
	v_mul_f32_e32 v0, v0, v4
	v_mul_f32_e32 v4, 0xbfb8aa3b, v14
	v_mul_f32_e32 v12, 0xbfb8aa3b, v15
	v_exp_f32_e32 v4, v4
	v_exp_f32_e32 v12, v12
	v_mul_f32_e32 v1, v13, v21
	v_mul_f32_e32 v1, v1, v5
	v_add_f32_e32 v4, 1.0, v4
	v_add_f32_e32 v5, 1.0, v12
	v_rcp_f32_e32 v4, v4
	v_rcp_f32_e32 v5, v5
	v_pk_mul_f32 v[8:9], v[136:137], v[8:9] op_sel_hi:[0,1]
	v_pk_mul_f32 v[6:7], v[136:137], v[6:7] op_sel_hi:[0,1]
	v_cvt_pk_bf16_f32 v0, v0, v1
	v_mul_f32_e32 v1, v14, v4
	v_mul_f32_e32 v4, v15, v5
	v_mul_f32_e32 v5, 0xbfb8aa3b, v8
	v_mul_f32_e32 v1, v1, v6
	v_exp_f32_e32 v5, v5
	v_mul_f32_e32 v6, 0xbfb8aa3b, v9
	v_exp_f32_e32 v6, v6
	v_pk_mul_f32 v[10:11], v[136:137], v[10:11] op_sel_hi:[0,1]
	v_add_f32_e32 v5, 1.0, v5
	v_rcp_f32_e32 v5, v5
	v_add_f32_e32 v6, 1.0, v6
	v_rcp_f32_e32 v6, v6
	v_mul_f32_e32 v4, v4, v7
	v_cvt_pk_bf16_f32 v1, v1, v4
	v_mul_f32_e32 v4, v8, v5
	v_mul_f32_e32 v5, 0xbfb8aa3b, v10
	v_mul_f32_e32 v2, v4, v2
	v_mul_f32_e32 v4, v9, v6
	v_exp_f32_e32 v5, v5
	v_mul_f32_e32 v6, 0xbfb8aa3b, v11
	v_exp_f32_e32 v6, v6
	v_mul_f32_e32 v3, v4, v3
	v_add_f32_e32 v4, 1.0, v5
	v_rcp_f32_e32 v4, v4
	v_add_f32_e32 v5, 1.0, v6
	v_rcp_f32_e32 v5, v5
	v_add_u32_e32 v16, 0xb0, v161
	v_mad_i64_i32 v[16:17], s[10:11], v16, s61, v[164:165]
	v_cvt_pk_bf16_f32 v2, v2, v3
	v_mul_f32_e32 v3, v10, v4
	v_lshl_add_u64 v[16:17], v[16:17], 0, v[166:167]
	v_mul_f32_e32 v3, v3, v18
	v_mul_f32_e32 v4, v11, v5
	s_andn2_b64 vcc, exec, s[0:1]
	s_mov_b64 s[0:1], -1
	v_mul_f32_e32 v4, v4, v19
	v_cvt_pk_bf16_f32 v3, v3, v4
	global_store_dwordx4 v[16:17], v[0:3], off
	s_cbranch_vccnz .LBB0_696
; #define PG8_BAR __builtin_amdgcn_s_barrier()
;     __device__ __forceinline__ void pre(const Unit& u, int wr, int fr, float (&rv)[8]) const {
; #pragma unroll
;         for (int i = 0; i < 8; ++i) rv[i] = rs[u.pm * BM + wr * 64 + fr + (i >> 2) * HALF + (i & 3) * 16];
;     }
; template <class Epi, class Sched, bool ALIGN_EPI = false, bool SP2 = false>
; __device__ __forceinline__ void gemm_phase(PG8_LAS unsigned char* lds, const Gemm g, const Sched& S, const Epi& E) {
;     ...
;         E.pre(cur, wr, fr, epre);
;         if constexpr (ALIGN_EPI) { if (wr == 1) PG8_BAR; }
	s_nop 0
	v_lshl_add_u32 v0, s36, 8, v137
	v_ashrrev_i32_e32 v1, 31, v0
	v_lshl_add_u64 v[0:1], v[0:1], 2, s[16:17]
	global_load_dword v162, v[0:1], off
	global_load_dword v160, v[0:1], off offset:64
	global_load_dword v158, v[0:1], off offset:128
	global_load_dword v156, v[0:1], off offset:192
	global_load_dword v154, v[0:1], off offset:512
	global_load_dword v152, v[0:1], off offset:576
	global_load_dword v146, v[0:1], off offset:640
	global_load_dword v136, v[0:1], off offset:704
	s_andn2_b64 vcc, exec, s[4:5]
	s_cbranch_vccnz .LBB0_695
	s_barrier
	s_branch .LBB0_695
